# sample GEMM operands via full-line LDS-DMA + XCD-aware sample tile map + XCD barrier at first seam + counted vmcnt in prompt scans
# speedup vs baseline: 1.0412x; 1.0378x over previous
; #define LAS __attribute__((address_space(3)))
; template <bool GATE>
; __device__ __forceinline__ void sample_gemm_res(LAS unsigned char* lds, const bf16* Amat, const bf16* Bt, const bf16* Hin, bf16* Hout, float* rss_out, const bf16* PP, const float* rss_in, int bid, int tid) {
;     const int wave = tid >> 6, lane = tid & 63, lr = lane & 15, kg = lane >> 4;
;   for (int tile = bid; tile < 256; tile += (int)gridDim.x) {
;     const int m0 = TP + (tile & 7) * 64, n0 = (tile >> 3) * 64;
;     const bf16x8* ap = (const bf16x8*)(Amat + (size_t)(m0 + lr) * 2048 + wave * 256 + 8 * kg);
;     const bf16x8* bp = (const bf16x8*)(Bt + (size_t)(n0 + lr) * 2048 + wave * 256 + 8 * kg);
;     const int erow = m0 + (tid >> 3); const size_t ep = (size_t)erow * 2048 + n0 + (tid & 7) * 8;
.LBB0_64:
	v_mov_b32_e32 v0, v183
	s_and_b64 vcc, exec, s[40:41]
	s_cbranch_vccnz .LBB0_71
	v_and_b32_e32 v8, 64, v216
	v_xor_b32_e32 v7, 1, v216
	v_add_u32_e32 v8, 64, v8
	v_cmp_lt_i32_e32 vcc, v7, v8
	s_waitcnt vmcnt(0)
	v_and_b32_e32 v75, 15, v0
	v_bfe_u32 v4, v0, 4, 2
	v_cndmask_b32_e32 v7, v216, v7, vcc
	v_lshlrev_b32_e32 v90, 2, v7
	v_xor_b32_e32 v7, 2, v216
	v_lshlrev_b32_e32 v2, 2, v0
	v_ashrrev_i32_e32 v88, 3, v0
	v_and_b32_e32 v5, 7, v0
	v_and_b32_e32 v0, 0x3fffffc0, v0
	v_cmp_lt_i32_e32 vcc, v7, v8
	v_lshl_or_b32 v0, v4, 2, v0
	s_load_dwordx2 s[0:1], s[60:61], 0x148
	v_cndmask_b32_e32 v7, v216, v7, vcc
	v_and_b32_e32 v2, 0xffffff00, v2
	v_lshlrev_b32_e32 v6, 2, v75
	v_lshlrev_b32_e32 v91, 2, v7
	v_xor_b32_e32 v7, 4, v216
	v_mul_lo_u32 v0, v0, s30
	s_waitcnt lgkmcnt(0)
	v_ashrrev_i32_e32 v3, 31, v2
	v_cmp_lt_i32_e32 vcc, v7, v8
	v_add3_u32 v93, 0, v6, v0
	v_lshlrev_b32_e32 v0, 4, v4
	v_lshlrev_b32_e32 v74, 3, v5
	v_lshl_add_u32 v89, v5, 5, 0
	v_cndmask_b32_e32 v7, v216, v7, vcc
	v_cmp_eq_u32_e32 vcc, 0, v5
	v_mul_lo_u32 v94, v88, s30
	v_lshl_add_u64 v[4:5], s[56:57], 0, v[0:1]
	v_lshlrev_b64 v[2:3], 1, v[2:3]
	v_lshlrev_b32_e32 v92, 2, v7
	v_add_u32_e32 v6, 0x10400, v94
	v_add_u32_e32 v7, 0x14500, v94
	v_add_u32_e32 v8, 0x18600, v94
	v_add_u32_e32 v9, 0x1c700, v94
	v_lshl_add_u64 v[4:5], v[4:5], 0, v[2:3]
	v_or_b32_e32 v2, v2, v0
	v_readlane_b32 s6, v254, 39
	v_lshl_add_u64 v[76:77], s[0:1], 0, v[4:5]
	v_lshl_add_u64 v[78:79], s[0:1], 0, v[2:3]
	v_or_b32_e32 v95, 0x2000, v75
	s_lshl_b32 s2, s6, 6
	v_add_u32_e32 v96, v89, v6
	v_add_u32_e32 v97, v89, v7
	v_add_u32_e32 v98, v89, v8
	v_add_u32_e32 v99, v89, v9
	s_and_b32 s4, s6, 7
	s_lshr_b32 s5, s6, 3
	s_lshl_b32 s4, s4, 2
	s_lshr_b32 s2, s5, 3
	s_add_i32 s4, s4, s2
	s_and_b32 s5, s5, 7
	s_lshl_b32 s4, s4, 3
	s_or_b32 s6, s4, s5
	s_lshl_b32 s2, s6, 6
	s_lshl_b32 s3, s6, 3
	s_branch .LBB0_67

; template <bool GATE>
; __device__ __forceinline__ void sample_gemm_res(LAS unsigned char* lds, const bf16* Amat, const bf16* Bt, const bf16* Hin, bf16* Hout, float* rss_out, const bf16* PP, const float* rss_in, int bid, int tid) {
;     ...
;   for (int tile = bid; tile < 256; tile += (int)gridDim.x) {
;     const int m0 = TP + (tile & 7) * 64, n0 = (tile >> 3) * 64;
;     const bf16x8* ap = (const bf16x8*)(Amat + (size_t)(m0 + lr) * 2048 + wave * 256 + 8 * kg);
;     const bf16x8* bp = (const bf16x8*)(Bt + (size_t)(n0 + lr) * 2048 + wave * 256 + 8 * kg);
;     const int erow = m0 + (tid >> 3); const size_t ep = (size_t)erow * 2048 + n0 + (tid & 7) * 8;
;     const u32x4 hw = *(const u32x4*)(Hin + ep); u32x4 pw = (u32x4){0u, 0u, 0u, 0u}; float rsi = 0.f; if (GATE) { pw = *(const u32x4*)(PP + ep); rsi = rss_in[erow]; }
;     f32x4m acc[4][4];
; #pragma unroll
;     for (int mi = 0; mi < 4; ++mi)
; #pragma unroll
;         for (int ni = 0; ni < 4; ++ni) acc[mi][ni] = (f32x4m){0.f, 0.f, 0.f, 0.f};
; #pragma unroll 2
;     for (int ks = 0; ks < 8; ++ks) { bf16x8 a[4], b[4];
; #pragma unroll
;         for (int q = 0; q < 4; ++q) { a[q] = ap[(size_t)q * 16 * 256 + ks * 4]; b[q] = bp[(size_t)q * 16 * 256 + ks * 4]; }
; #pragma unroll
;         for (int mi = 0; mi < 4; ++mi)
; #pragma unroll
;             for (int ni = 0; ni < 4; ++ni) acc[mi][ni] = __builtin_amdgcn_mfma_f32_16x16x32_bf16(a[mi], b[ni], acc[mi][ni], 0, 0, 0); }
.LBB0_67:
	s_lshl_b32 s0, s6, 6
	s_and_b32 s1, s0, 0x1c0
	v_add_u32_e32 v0, s1, v88
	s_lshl_b32 s0, s6, 3
	v_add_u32_e32 v80, 0x2000, v0
	s_andn2_b32 s0, s0, 63
	v_ashrrev_i32_e32 v81, 31, v80
	v_lshlrev_b64 v[2:3], 11, v[80:81]
	s_ashr_i32 s1, s0, 31
	v_lshl_add_u64 v[82:83], v[2:3], 0, s[0:1]
	v_or_b32_e32 v82, v82, v74
	v_lshlrev_b64 v[2:3], 1, v[82:83]
	v_lshl_add_u64 v[4:5], s[46:47], 0, v[2:3]
	v_lshl_add_u64 v[2:3], s[52:53], 0, v[2:3]
	v_lshl_add_u64 v[10:11], v[80:81], 2, s[54:55]
	global_load_dwordx4 v[6:9], v[4:5], off
	s_nop 0
	global_load_dwordx4 v[2:5], v[2:3], off
	s_and_b32 s0, s3, 0xffffffc0
	global_load_dword v100, v[10:11], off
	v_or_b32_e32 v10, s0, v75
	v_ashrrev_i32_e32 v11, 31, v10
	v_lshlrev_b64 v[10:11], 12, v[10:11]
	s_and_b32 s0, s2, 0x1c0
	v_lshl_add_u64 v[84:85], v[76:77], 0, v[10:11]
	v_add_lshl_u32 v0, v95, s0, 12
	v_mov_b32_e32 v10, 0
	v_lshl_add_u64 v[86:87], v[78:79], 0, v[0:1]
	s_mov_b64 s[4:5], 0
	v_mov_b32_e32 v11, v10
	v_mov_b32_e32 v12, v10
	v_mov_b32_e32 v13, v10
	v_mov_b32_e32 v14, v10
	v_mov_b32_e32 v15, v10
	v_mov_b32_e32 v16, v10
	v_mov_b32_e32 v17, v10
	v_mov_b32_e32 v18, v10
	v_mov_b32_e32 v19, v10
	v_mov_b32_e32 v20, v10
	v_mov_b32_e32 v21, v10
	v_mov_b32_e32 v22, v10
	v_mov_b32_e32 v23, v10
	v_mov_b32_e32 v24, v10
	v_mov_b32_e32 v25, v10
	v_mov_b32_e32 v26, v10
	v_mov_b32_e32 v27, v10
	v_mov_b32_e32 v28, v10
	v_mov_b32_e32 v29, v10
	v_mov_b32_e32 v34, v10
	v_mov_b32_e32 v35, v10
	v_mov_b32_e32 v36, v10
	v_mov_b32_e32 v37, v10
	v_mov_b32_e32 v30, v10
	v_mov_b32_e32 v31, v10
	v_mov_b32_e32 v32, v10
	v_mov_b32_e32 v33, v10
	v_mov_b32_e32 v38, v10
	v_mov_b32_e32 v39, v10
	v_mov_b32_e32 v40, v10
	v_mov_b32_e32 v41, v10
	v_mov_b32_e32 v42, v10
	v_mov_b32_e32 v43, v10
	v_mov_b32_e32 v44, v10
	v_mov_b32_e32 v45, v10
	v_mov_b32_e32 v50, v10
	v_mov_b32_e32 v51, v10
	v_mov_b32_e32 v52, v10
	v_mov_b32_e32 v53, v10
	v_mov_b32_e32 v46, v10
	v_mov_b32_e32 v47, v10
	v_mov_b32_e32 v48, v10
	v_mov_b32_e32 v49, v10
	v_mov_b32_e32 v58, v10
	v_mov_b32_e32 v59, v10
	v_mov_b32_e32 v60, v10
	v_mov_b32_e32 v61, v10
	v_mov_b32_e32 v54, v10
	v_mov_b32_e32 v55, v10
	v_mov_b32_e32 v56, v10
	v_mov_b32_e32 v57, v10
	v_mov_b32_e32 v66, v10
	v_mov_b32_e32 v67, v10
	v_mov_b32_e32 v68, v10
	v_mov_b32_e32 v69, v10
	v_mov_b32_e32 v62, v10
	v_mov_b32_e32 v63, v10
	v_mov_b32_e32 v64, v10
	v_mov_b32_e32 v65, v10
	v_mov_b32_e32 v70, v10
	v_mov_b32_e32 v71, v10
	v_mov_b32_e32 v72, v10
	v_mov_b32_e32 v73, v10
	v_readfirstlane_b32 s8, v86
	v_readfirstlane_b32 s9, v87
	v_readfirstlane_b32 s10, v84
	v_readfirstlane_b32 s11, v85
	s_add_u32 s8, s8, 0x22200000
	s_addc_u32 s9, s9, 0
	s_add_u32 s10, s10, 0x8200000
	s_addc_u32 s11, s11, 0
	v_lshrrev_b32_e32 v212, 3, v216
	v_and_b32_e32 v213, 7, v216
	v_xor_b32_e32 v213, v213, v212
	v_lshlrev_b32_e32 v213, 4, v213
	v_lshl_or_b32 v248, v212, 12, v213
	v_and_b32_e32 v212, 15, v216
	v_lshrrev_b32_e32 v213, 4, v216
	v_and_b32_e32 v249, 7, v212
	v_xor_b32_e32 v213, v213, v249
	v_lshlrev_b32_e32 v213, 4, v213
	v_lshl_or_b32 v249, v212, 7, v213
	v_lshrrev_b32_e32 v212, 6, v183
	s_nop 0
	v_readfirstlane_b32 s7, v212
	s_lshl_b32 s7, s7, 14
	v_add_u32_e32 v249, s7, v249
	v_xor_b32_e32 v250, 64, v249
	s_add_i32 m0, s7, 0x0
	s_add_u32 s4, s8, 0x0
	s_addc_u32 s5, s9, 0
	global_load_lds_dwordx4 v248, s[4:5]
	s_add_i32 m0, s7, 0x400
	s_add_u32 s4, s8, 0x8000
	s_addc_u32 s5, s9, 0
	global_load_lds_dwordx4 v248, s[4:5]
	s_add_i32 m0, s7, 0x800
	s_add_u32 s4, s8, 0x10000
	s_addc_u32 s5, s9, 0
	global_load_lds_dwordx4 v248, s[4:5]
	s_add_i32 m0, s7, 0xc00
	s_add_u32 s4, s8, 0x18000
	s_addc_u32 s5, s9, 0
	global_load_lds_dwordx4 v248, s[4:5]
	s_add_i32 m0, s7, 0x1000
	s_add_u32 s4, s8, 0x20000
	s_addc_u32 s5, s9, 0
	global_load_lds_dwordx4 v248, s[4:5]
	s_add_i32 m0, s7, 0x1400
	s_add_u32 s4, s8, 0x28000
	s_addc_u32 s5, s9, 0
	global_load_lds_dwordx4 v248, s[4:5]
	s_add_i32 m0, s7, 0x1800
	s_add_u32 s4, s8, 0x30000
	s_addc_u32 s5, s9, 0
	global_load_lds_dwordx4 v248, s[4:5]
	s_add_i32 m0, s7, 0x1c00
	s_add_u32 s4, s8, 0x38000
	s_addc_u32 s5, s9, 0
	global_load_lds_dwordx4 v248, s[4:5]
	s_add_i32 m0, s7, 0x2000
	s_add_u32 s4, s10, 0x0
	s_addc_u32 s5, s11, 0
	global_load_lds_dwordx4 v248, s[4:5]
	s_add_i32 m0, s7, 0x2400
	s_add_u32 s4, s10, 0x8000
	s_addc_u32 s5, s11, 0
	global_load_lds_dwordx4 v248, s[4:5]
	s_add_i32 m0, s7, 0x2800
	s_add_u32 s4, s10, 0x10000
	s_addc_u32 s5, s11, 0
	global_load_lds_dwordx4 v248, s[4:5]
	s_add_i32 m0, s7, 0x2c00
	s_add_u32 s4, s10, 0x18000
	s_addc_u32 s5, s11, 0
	global_load_lds_dwordx4 v248, s[4:5]
	s_add_i32 m0, s7, 0x3000
	s_add_u32 s4, s10, 0x20000
	s_addc_u32 s5, s11, 0
	global_load_lds_dwordx4 v248, s[4:5]
	s_add_i32 m0, s7, 0x3400
	s_add_u32 s4, s10, 0x28000
	s_addc_u32 s5, s11, 0
	global_load_lds_dwordx4 v248, s[4:5]
	s_add_i32 m0, s7, 0x3800
	s_add_u32 s4, s10, 0x30000
	s_addc_u32 s5, s11, 0
	global_load_lds_dwordx4 v248, s[4:5]
	s_add_i32 m0, s7, 0x3c00
	s_add_u32 s4, s10, 0x38000
	s_addc_u32 s5, s11, 0
	global_load_lds_dwordx4 v248, s[4:5]
	s_waitcnt vmcnt(0)
	ds_read_b128 v[102:105], v249 offset:0
	ds_read_b128 v[106:109], v250 offset:0
	ds_read_b128 v[110:113], v249 offset:2048
	ds_read_b128 v[114:117], v250 offset:2048
	ds_read_b128 v[118:121], v249 offset:4096
	ds_read_b128 v[122:125], v250 offset:4096
	ds_read_b128 v[126:129], v249 offset:6144
	ds_read_b128 v[130:133], v250 offset:6144
	ds_read_b128 v[150:153], v249 offset:8192
	ds_read_b128 v[154:157], v250 offset:8192
	ds_read_b128 v[158:161], v249 offset:10240
	ds_read_b128 v[162:165], v250 offset:10240
	ds_read_b128 v[166:169], v249 offset:12288
	ds_read_b128 v[170:173], v250 offset:12288
	ds_read_b128 v[174:177], v249 offset:14336
	ds_read_b128 v[178:181], v250 offset:14336
	s_waitcnt lgkmcnt(0)
; template <bool GATE>
; __device__ __forceinline__ void sample_gemm_res(LAS unsigned char* lds, const bf16* Amat, const bf16* Bt, const bf16* Hin, bf16* Hout, float* rss_out, const bf16* PP, const float* rss_in, int bid, int tid) {
;     ...
;     for (int ks = 0; ks < 8; ++ks) { bf16x8 a[4], b[4];
; #pragma unroll
;         for (int q = 0; q < 4; ++q) { a[q] = ap[(size_t)q * 16 * 256 + ks * 4]; b[q] = bp[(size_t)q * 16 * 256 + ks * 4]; }
; #pragma unroll
;         for (int mi = 0; mi < 4; ++mi)
; #pragma unroll
;             for (int ni = 0; ni < 4; ++ni) acc[mi][ni] = __builtin_amdgcn_mfma_f32_16x16x32_bf16(a[mi], b[ni], acc[mi][ni], 0, 0, 0); }
	s_add_i32 m0, s7, 0x0
	s_add_u32 s4, s8, 0x80
	s_addc_u32 s5, s9, 0
	global_load_lds_dwordx4 v248, s[4:5]
	s_add_i32 m0, s7, 0x400
	s_add_u32 s4, s8, 0x8080
	s_addc_u32 s5, s9, 0
	global_load_lds_dwordx4 v248, s[4:5]
	s_add_i32 m0, s7, 0x800
	s_add_u32 s4, s8, 0x10080
	s_addc_u32 s5, s9, 0
	global_load_lds_dwordx4 v248, s[4:5]
	s_add_i32 m0, s7, 0xc00
	s_add_u32 s4, s8, 0x18080
	s_addc_u32 s5, s9, 0
	global_load_lds_dwordx4 v248, s[4:5]
	s_add_i32 m0, s7, 0x1000
	s_add_u32 s4, s8, 0x20080
	s_addc_u32 s5, s9, 0
	global_load_lds_dwordx4 v248, s[4:5]
	s_add_i32 m0, s7, 0x1400
	s_add_u32 s4, s8, 0x28080
	s_addc_u32 s5, s9, 0
	global_load_lds_dwordx4 v248, s[4:5]
	s_add_i32 m0, s7, 0x1800
	s_add_u32 s4, s8, 0x30080
	s_addc_u32 s5, s9, 0
	global_load_lds_dwordx4 v248, s[4:5]
	s_add_i32 m0, s7, 0x1c00
	s_add_u32 s4, s8, 0x38080
	s_addc_u32 s5, s9, 0
	global_load_lds_dwordx4 v248, s[4:5]
	s_add_i32 m0, s7, 0x2000
	s_add_u32 s4, s10, 0x80
	s_addc_u32 s5, s11, 0
	global_load_lds_dwordx4 v248, s[4:5]
	s_add_i32 m0, s7, 0x2400
	s_add_u32 s4, s10, 0x8080
	s_addc_u32 s5, s11, 0
	global_load_lds_dwordx4 v248, s[4:5]
	s_add_i32 m0, s7, 0x2800
	s_add_u32 s4, s10, 0x10080
	s_addc_u32 s5, s11, 0
	global_load_lds_dwordx4 v248, s[4:5]
	s_add_i32 m0, s7, 0x2c00
	s_add_u32 s4, s10, 0x18080
	s_addc_u32 s5, s11, 0
	global_load_lds_dwordx4 v248, s[4:5]
	s_add_i32 m0, s7, 0x3000
	s_add_u32 s4, s10, 0x20080
	s_addc_u32 s5, s11, 0
	global_load_lds_dwordx4 v248, s[4:5]
	s_add_i32 m0, s7, 0x3400
	s_add_u32 s4, s10, 0x28080
	s_addc_u32 s5, s11, 0
	global_load_lds_dwordx4 v248, s[4:5]
	s_add_i32 m0, s7, 0x3800
	s_add_u32 s4, s10, 0x30080
	s_addc_u32 s5, s11, 0
	global_load_lds_dwordx4 v248, s[4:5]
	s_add_i32 m0, s7, 0x3c00
	s_add_u32 s4, s10, 0x38080
	s_addc_u32 s5, s11, 0
	global_load_lds_dwordx4 v248, s[4:5]
	v_mfma_f32_16x16x32_bf16 v[10:13], v[102:105], v[150:153], v[10:13]
	v_mfma_f32_16x16x32_bf16 v[14:17], v[102:105], v[158:161], v[14:17]
	v_mfma_f32_16x16x32_bf16 v[18:21], v[102:105], v[166:169], v[18:21]
	v_mfma_f32_16x16x32_bf16 v[22:25], v[102:105], v[174:177], v[22:25]
	v_mfma_f32_16x16x32_bf16 v[26:29], v[110:113], v[150:153], v[26:29]
	v_mfma_f32_16x16x32_bf16 v[34:37], v[110:113], v[158:161], v[34:37]
	v_mfma_f32_16x16x32_bf16 v[30:33], v[110:113], v[166:169], v[30:33]
	v_mfma_f32_16x16x32_bf16 v[38:41], v[110:113], v[174:177], v[38:41]
	v_mfma_f32_16x16x32_bf16 v[42:45], v[118:121], v[150:153], v[42:45]
	v_mfma_f32_16x16x32_bf16 v[50:53], v[118:121], v[158:161], v[50:53]
	v_mfma_f32_16x16x32_bf16 v[46:49], v[118:121], v[166:169], v[46:49]
	v_mfma_f32_16x16x32_bf16 v[58:61], v[118:121], v[174:177], v[58:61]
	v_mfma_f32_16x16x32_bf16 v[54:57], v[126:129], v[150:153], v[54:57]
	v_mfma_f32_16x16x32_bf16 v[66:69], v[126:129], v[158:161], v[66:69]
	v_mfma_f32_16x16x32_bf16 v[62:65], v[126:129], v[166:169], v[62:65]
	v_mfma_f32_16x16x32_bf16 v[70:73], v[126:129], v[174:177], v[70:73]
	v_mfma_f32_16x16x32_bf16 v[10:13], v[106:109], v[154:157], v[10:13]
	v_mfma_f32_16x16x32_bf16 v[14:17], v[106:109], v[162:165], v[14:17]
	v_mfma_f32_16x16x32_bf16 v[18:21], v[106:109], v[170:173], v[18:21]
	v_mfma_f32_16x16x32_bf16 v[22:25], v[106:109], v[178:181], v[22:25]
	v_mfma_f32_16x16x32_bf16 v[26:29], v[114:117], v[154:157], v[26:29]
	v_mfma_f32_16x16x32_bf16 v[34:37], v[114:117], v[162:165], v[34:37]
	v_mfma_f32_16x16x32_bf16 v[30:33], v[114:117], v[170:173], v[30:33]
	v_mfma_f32_16x16x32_bf16 v[38:41], v[114:117], v[178:181], v[38:41]
	v_mfma_f32_16x16x32_bf16 v[42:45], v[122:125], v[154:157], v[42:45]
	v_mfma_f32_16x16x32_bf16 v[50:53], v[122:125], v[162:165], v[50:53]
	v_mfma_f32_16x16x32_bf16 v[46:49], v[122:125], v[170:173], v[46:49]
	v_mfma_f32_16x16x32_bf16 v[58:61], v[122:125], v[178:181], v[58:61]
	v_mfma_f32_16x16x32_bf16 v[54:57], v[130:133], v[154:157], v[54:57]
	v_mfma_f32_16x16x32_bf16 v[66:69], v[130:133], v[162:165], v[66:69]
	v_mfma_f32_16x16x32_bf16 v[62:65], v[130:133], v[170:173], v[62:65]
	v_mfma_f32_16x16x32_bf16 v[70:73], v[130:133], v[178:181], v[70:73]
	s_waitcnt vmcnt(0)
	ds_read_b128 v[102:105], v249 offset:0
	ds_read_b128 v[106:109], v250 offset:0
	ds_read_b128 v[110:113], v249 offset:2048
	ds_read_b128 v[114:117], v250 offset:2048
	ds_read_b128 v[118:121], v249 offset:4096
	ds_read_b128 v[122:125], v250 offset:4096
	ds_read_b128 v[126:129], v249 offset:6144
	ds_read_b128 v[130:133], v250 offset:6144
	ds_read_b128 v[150:153], v249 offset:8192
	ds_read_b128 v[154:157], v250 offset:8192
	ds_read_b128 v[158:161], v249 offset:10240
	ds_read_b128 v[162:165], v250 offset:10240
	ds_read_b128 v[166:169], v249 offset:12288
	ds_read_b128 v[170:173], v250 offset:12288
	ds_read_b128 v[174:177], v249 offset:14336
	ds_read_b128 v[178:181], v250 offset:14336
	s_waitcnt lgkmcnt(0)
; template <bool GATE>
; __device__ __forceinline__ void sample_gemm_res(LAS unsigned char* lds, const bf16* Amat, const bf16* Bt, const bf16* Hin, bf16* Hout, float* rss_out, const bf16* PP, const float* rss_in, int bid, int tid) {
;     ...
;     for (int ks = 0; ks < 8; ++ks) { bf16x8 a[4], b[4];
; #pragma unroll
;         for (int q = 0; q < 4; ++q) { a[q] = ap[(size_t)q * 16 * 256 + ks * 4]; b[q] = bp[(size_t)q * 16 * 256 + ks * 4]; }
; #pragma unroll
;         for (int mi = 0; mi < 4; ++mi)
; #pragma unroll
;             for (int ni = 0; ni < 4; ++ni) acc[mi][ni] = __builtin_amdgcn_mfma_f32_16x16x32_bf16(a[mi], b[ni], acc[mi][ni], 0, 0, 0); }
	s_add_i32 m0, s7, 0x0
	s_add_u32 s4, s8, 0x100
	s_addc_u32 s5, s9, 0
	global_load_lds_dwordx4 v248, s[4:5]
	s_add_i32 m0, s7, 0x400
	s_add_u32 s4, s8, 0x8100
	s_addc_u32 s5, s9, 0
	global_load_lds_dwordx4 v248, s[4:5]
	s_add_i32 m0, s7, 0x800
	s_add_u32 s4, s8, 0x10100
	s_addc_u32 s5, s9, 0
	global_load_lds_dwordx4 v248, s[4:5]
	s_add_i32 m0, s7, 0xc00
	s_add_u32 s4, s8, 0x18100
	s_addc_u32 s5, s9, 0
	global_load_lds_dwordx4 v248, s[4:5]
	s_add_i32 m0, s7, 0x1000
	s_add_u32 s4, s8, 0x20100
	s_addc_u32 s5, s9, 0
	global_load_lds_dwordx4 v248, s[4:5]
	s_add_i32 m0, s7, 0x1400
	s_add_u32 s4, s8, 0x28100
	s_addc_u32 s5, s9, 0
	global_load_lds_dwordx4 v248, s[4:5]
	s_add_i32 m0, s7, 0x1800
	s_add_u32 s4, s8, 0x30100
	s_addc_u32 s5, s9, 0
	global_load_lds_dwordx4 v248, s[4:5]
	s_add_i32 m0, s7, 0x1c00
	s_add_u32 s4, s8, 0x38100
	s_addc_u32 s5, s9, 0
	global_load_lds_dwordx4 v248, s[4:5]
	s_add_i32 m0, s7, 0x2000
	s_add_u32 s4, s10, 0x100
	s_addc_u32 s5, s11, 0
	global_load_lds_dwordx4 v248, s[4:5]
	s_add_i32 m0, s7, 0x2400
	s_add_u32 s4, s10, 0x8100
	s_addc_u32 s5, s11, 0
	global_load_lds_dwordx4 v248, s[4:5]
	s_add_i32 m0, s7, 0x2800
	s_add_u32 s4, s10, 0x10100
	s_addc_u32 s5, s11, 0
	global_load_lds_dwordx4 v248, s[4:5]
	s_add_i32 m0, s7, 0x2c00
	s_add_u32 s4, s10, 0x18100
	s_addc_u32 s5, s11, 0
	global_load_lds_dwordx4 v248, s[4:5]
	s_add_i32 m0, s7, 0x3000
	s_add_u32 s4, s10, 0x20100
	s_addc_u32 s5, s11, 0
	global_load_lds_dwordx4 v248, s[4:5]
	s_add_i32 m0, s7, 0x3400
	s_add_u32 s4, s10, 0x28100
	s_addc_u32 s5, s11, 0
	global_load_lds_dwordx4 v248, s[4:5]
	s_add_i32 m0, s7, 0x3800
	s_add_u32 s4, s10, 0x30100
	s_addc_u32 s5, s11, 0
	global_load_lds_dwordx4 v248, s[4:5]
	s_add_i32 m0, s7, 0x3c00
	s_add_u32 s4, s10, 0x38100
	s_addc_u32 s5, s11, 0
	global_load_lds_dwordx4 v248, s[4:5]
	v_mfma_f32_16x16x32_bf16 v[10:13], v[102:105], v[150:153], v[10:13]
	v_mfma_f32_16x16x32_bf16 v[14:17], v[102:105], v[158:161], v[14:17]
	v_mfma_f32_16x16x32_bf16 v[18:21], v[102:105], v[166:169], v[18:21]
	v_mfma_f32_16x16x32_bf16 v[22:25], v[102:105], v[174:177], v[22:25]
	v_mfma_f32_16x16x32_bf16 v[26:29], v[110:113], v[150:153], v[26:29]
	v_mfma_f32_16x16x32_bf16 v[34:37], v[110:113], v[158:161], v[34:37]
	v_mfma_f32_16x16x32_bf16 v[30:33], v[110:113], v[166:169], v[30:33]
	v_mfma_f32_16x16x32_bf16 v[38:41], v[110:113], v[174:177], v[38:41]
	v_mfma_f32_16x16x32_bf16 v[42:45], v[118:121], v[150:153], v[42:45]
	v_mfma_f32_16x16x32_bf16 v[50:53], v[118:121], v[158:161], v[50:53]
	v_mfma_f32_16x16x32_bf16 v[46:49], v[118:121], v[166:169], v[46:49]
	v_mfma_f32_16x16x32_bf16 v[58:61], v[118:121], v[174:177], v[58:61]
	v_mfma_f32_16x16x32_bf16 v[54:57], v[126:129], v[150:153], v[54:57]
	v_mfma_f32_16x16x32_bf16 v[66:69], v[126:129], v[158:161], v[66:69]
	v_mfma_f32_16x16x32_bf16 v[62:65], v[126:129], v[166:169], v[62:65]
	v_mfma_f32_16x16x32_bf16 v[70:73], v[126:129], v[174:177], v[70:73]
	v_mfma_f32_16x16x32_bf16 v[10:13], v[106:109], v[154:157], v[10:13]
	v_mfma_f32_16x16x32_bf16 v[14:17], v[106:109], v[162:165], v[14:17]
	v_mfma_f32_16x16x32_bf16 v[18:21], v[106:109], v[170:173], v[18:21]
	v_mfma_f32_16x16x32_bf16 v[22:25], v[106:109], v[178:181], v[22:25]
	v_mfma_f32_16x16x32_bf16 v[26:29], v[114:117], v[154:157], v[26:29]
	v_mfma_f32_16x16x32_bf16 v[34:37], v[114:117], v[162:165], v[34:37]
	v_mfma_f32_16x16x32_bf16 v[30:33], v[114:117], v[170:173], v[30:33]
	v_mfma_f32_16x16x32_bf16 v[38:41], v[114:117], v[178:181], v[38:41]
	v_mfma_f32_16x16x32_bf16 v[42:45], v[122:125], v[154:157], v[42:45]
	v_mfma_f32_16x16x32_bf16 v[50:53], v[122:125], v[162:165], v[50:53]
	v_mfma_f32_16x16x32_bf16 v[46:49], v[122:125], v[170:173], v[46:49]
	v_mfma_f32_16x16x32_bf16 v[58:61], v[122:125], v[178:181], v[58:61]
	v_mfma_f32_16x16x32_bf16 v[54:57], v[130:133], v[154:157], v[54:57]
	v_mfma_f32_16x16x32_bf16 v[66:69], v[130:133], v[162:165], v[66:69]
	v_mfma_f32_16x16x32_bf16 v[62:65], v[130:133], v[170:173], v[62:65]
	v_mfma_f32_16x16x32_bf16 v[70:73], v[130:133], v[178:181], v[70:73]
	s_waitcnt vmcnt(0)
	ds_read_b128 v[102:105], v249 offset:0
	ds_read_b128 v[106:109], v250 offset:0
	ds_read_b128 v[110:113], v249 offset:2048
	ds_read_b128 v[114:117], v250 offset:2048
	ds_read_b128 v[118:121], v249 offset:4096
	ds_read_b128 v[122:125], v250 offset:4096
	ds_read_b128 v[126:129], v249 offset:6144
	ds_read_b128 v[130:133], v250 offset:6144
	ds_read_b128 v[150:153], v249 offset:8192
	ds_read_b128 v[154:157], v250 offset:8192
	ds_read_b128 v[158:161], v249 offset:10240
	ds_read_b128 v[162:165], v250 offset:10240
	ds_read_b128 v[166:169], v249 offset:12288
	ds_read_b128 v[170:173], v250 offset:12288
	ds_read_b128 v[174:177], v249 offset:14336
	ds_read_b128 v[178:181], v250 offset:14336
	s_waitcnt lgkmcnt(0)
; #define LAS __attribute__((address_space(3)))
; template <bool GATE>
; __device__ __forceinline__ void sample_gemm_res(LAS unsigned char* lds, const bf16* Amat, const bf16* Bt, const bf16* Hin, bf16* Hout, float* rss_out, const bf16* PP, const float* rss_in, int bid, int tid) {
;     ...
;     for (int ks = 0; ks < 8; ++ks) { bf16x8 a[4], b[4];
; #pragma unroll
;         for (int q = 0; q < 4; ++q) { a[q] = ap[(size_t)q * 16 * 256 + ks * 4]; b[q] = bp[(size_t)q * 16 * 256 + ks * 4]; }
; #pragma unroll
;         for (int mi = 0; mi < 4; ++mi)
; #pragma unroll
;             for (int ni = 0; ni < 4; ++ni) acc[mi][ni] = __builtin_amdgcn_mfma_f32_16x16x32_bf16(a[mi], b[ni], acc[mi][ni], 0, 0, 0); }
;     LAS float* red = (LAS float*)lds;
;     __syncthreads();
	s_add_i32 m0, s7, 0x0
	s_add_u32 s4, s8, 0x180
	s_addc_u32 s5, s9, 0
	global_load_lds_dwordx4 v248, s[4:5]
	s_add_i32 m0, s7, 0x400
	s_add_u32 s4, s8, 0x8180
	s_addc_u32 s5, s9, 0
	global_load_lds_dwordx4 v248, s[4:5]
	s_add_i32 m0, s7, 0x800
	s_add_u32 s4, s8, 0x10180
	s_addc_u32 s5, s9, 0
	global_load_lds_dwordx4 v248, s[4:5]
	s_add_i32 m0, s7, 0xc00
	s_add_u32 s4, s8, 0x18180
	s_addc_u32 s5, s9, 0
	global_load_lds_dwordx4 v248, s[4:5]
	s_add_i32 m0, s7, 0x1000
	s_add_u32 s4, s8, 0x20180
	s_addc_u32 s5, s9, 0
	global_load_lds_dwordx4 v248, s[4:5]
	s_add_i32 m0, s7, 0x1400
	s_add_u32 s4, s8, 0x28180
	s_addc_u32 s5, s9, 0
	global_load_lds_dwordx4 v248, s[4:5]
	s_add_i32 m0, s7, 0x1800
	s_add_u32 s4, s8, 0x30180
	s_addc_u32 s5, s9, 0
	global_load_lds_dwordx4 v248, s[4:5]
	s_add_i32 m0, s7, 0x1c00
	s_add_u32 s4, s8, 0x38180
	s_addc_u32 s5, s9, 0
	global_load_lds_dwordx4 v248, s[4:5]
	s_add_i32 m0, s7, 0x2000
	s_add_u32 s4, s10, 0x180
	s_addc_u32 s5, s11, 0
	global_load_lds_dwordx4 v248, s[4:5]
	s_add_i32 m0, s7, 0x2400
	s_add_u32 s4, s10, 0x8180
	s_addc_u32 s5, s11, 0
	global_load_lds_dwordx4 v248, s[4:5]
	s_add_i32 m0, s7, 0x2800
	s_add_u32 s4, s10, 0x10180
	s_addc_u32 s5, s11, 0
	global_load_lds_dwordx4 v248, s[4:5]
	s_add_i32 m0, s7, 0x2c00
	s_add_u32 s4, s10, 0x18180
	s_addc_u32 s5, s11, 0
	global_load_lds_dwordx4 v248, s[4:5]
	s_add_i32 m0, s7, 0x3000
	s_add_u32 s4, s10, 0x20180
	s_addc_u32 s5, s11, 0
	global_load_lds_dwordx4 v248, s[4:5]
	s_add_i32 m0, s7, 0x3400
	s_add_u32 s4, s10, 0x28180
	s_addc_u32 s5, s11, 0
	global_load_lds_dwordx4 v248, s[4:5]
	s_add_i32 m0, s7, 0x3800
	s_add_u32 s4, s10, 0x30180
	s_addc_u32 s5, s11, 0
	global_load_lds_dwordx4 v248, s[4:5]
	s_add_i32 m0, s7, 0x3c00
	s_add_u32 s4, s10, 0x38180
	s_addc_u32 s5, s11, 0
	global_load_lds_dwordx4 v248, s[4:5]
	v_mfma_f32_16x16x32_bf16 v[10:13], v[102:105], v[150:153], v[10:13]
	v_mfma_f32_16x16x32_bf16 v[14:17], v[102:105], v[158:161], v[14:17]
	v_mfma_f32_16x16x32_bf16 v[18:21], v[102:105], v[166:169], v[18:21]
	v_mfma_f32_16x16x32_bf16 v[22:25], v[102:105], v[174:177], v[22:25]
	v_mfma_f32_16x16x32_bf16 v[26:29], v[110:113], v[150:153], v[26:29]
	v_mfma_f32_16x16x32_bf16 v[34:37], v[110:113], v[158:161], v[34:37]
	v_mfma_f32_16x16x32_bf16 v[30:33], v[110:113], v[166:169], v[30:33]
	v_mfma_f32_16x16x32_bf16 v[38:41], v[110:113], v[174:177], v[38:41]
	v_mfma_f32_16x16x32_bf16 v[42:45], v[118:121], v[150:153], v[42:45]
	v_mfma_f32_16x16x32_bf16 v[50:53], v[118:121], v[158:161], v[50:53]
	v_mfma_f32_16x16x32_bf16 v[46:49], v[118:121], v[166:169], v[46:49]
	v_mfma_f32_16x16x32_bf16 v[58:61], v[118:121], v[174:177], v[58:61]
	v_mfma_f32_16x16x32_bf16 v[54:57], v[126:129], v[150:153], v[54:57]
	v_mfma_f32_16x16x32_bf16 v[66:69], v[126:129], v[158:161], v[66:69]
	v_mfma_f32_16x16x32_bf16 v[62:65], v[126:129], v[166:169], v[62:65]
	v_mfma_f32_16x16x32_bf16 v[70:73], v[126:129], v[174:177], v[70:73]
	v_mfma_f32_16x16x32_bf16 v[10:13], v[106:109], v[154:157], v[10:13]
	v_mfma_f32_16x16x32_bf16 v[14:17], v[106:109], v[162:165], v[14:17]
	v_mfma_f32_16x16x32_bf16 v[18:21], v[106:109], v[170:173], v[18:21]
	v_mfma_f32_16x16x32_bf16 v[22:25], v[106:109], v[178:181], v[22:25]
	v_mfma_f32_16x16x32_bf16 v[26:29], v[114:117], v[154:157], v[26:29]
	v_mfma_f32_16x16x32_bf16 v[34:37], v[114:117], v[162:165], v[34:37]
	v_mfma_f32_16x16x32_bf16 v[30:33], v[114:117], v[170:173], v[30:33]
	v_mfma_f32_16x16x32_bf16 v[38:41], v[114:117], v[178:181], v[38:41]
	v_mfma_f32_16x16x32_bf16 v[42:45], v[122:125], v[154:157], v[42:45]
	v_mfma_f32_16x16x32_bf16 v[50:53], v[122:125], v[162:165], v[50:53]
	v_mfma_f32_16x16x32_bf16 v[46:49], v[122:125], v[170:173], v[46:49]
	v_mfma_f32_16x16x32_bf16 v[58:61], v[122:125], v[178:181], v[58:61]
	v_mfma_f32_16x16x32_bf16 v[54:57], v[130:133], v[154:157], v[54:57]
	v_mfma_f32_16x16x32_bf16 v[66:69], v[130:133], v[162:165], v[66:69]
	v_mfma_f32_16x16x32_bf16 v[62:65], v[130:133], v[170:173], v[62:65]
	v_mfma_f32_16x16x32_bf16 v[70:73], v[130:133], v[178:181], v[70:73]
	s_waitcnt vmcnt(0)
	ds_read_b128 v[102:105], v249 offset:0
	ds_read_b128 v[106:109], v250 offset:0
	ds_read_b128 v[110:113], v249 offset:2048
	ds_read_b128 v[114:117], v250 offset:2048
	ds_read_b128 v[118:121], v249 offset:4096
	ds_read_b128 v[122:125], v250 offset:4096
	ds_read_b128 v[126:129], v249 offset:6144
	ds_read_b128 v[130:133], v250 offset:6144
	ds_read_b128 v[150:153], v249 offset:8192
	ds_read_b128 v[154:157], v250 offset:8192
	ds_read_b128 v[158:161], v249 offset:10240
	ds_read_b128 v[162:165], v250 offset:10240
	ds_read_b128 v[166:169], v249 offset:12288
	ds_read_b128 v[170:173], v250 offset:12288
	ds_read_b128 v[174:177], v249 offset:14336
	ds_read_b128 v[178:181], v250 offset:14336
	s_waitcnt lgkmcnt(0)
	v_mfma_f32_16x16x32_bf16 v[10:13], v[102:105], v[150:153], v[10:13]
	v_mfma_f32_16x16x32_bf16 v[14:17], v[102:105], v[158:161], v[14:17]
	v_mfma_f32_16x16x32_bf16 v[18:21], v[102:105], v[166:169], v[18:21]
	v_mfma_f32_16x16x32_bf16 v[22:25], v[102:105], v[174:177], v[22:25]
	v_mfma_f32_16x16x32_bf16 v[26:29], v[110:113], v[150:153], v[26:29]
	v_mfma_f32_16x16x32_bf16 v[34:37], v[110:113], v[158:161], v[34:37]
	v_mfma_f32_16x16x32_bf16 v[30:33], v[110:113], v[166:169], v[30:33]
	v_mfma_f32_16x16x32_bf16 v[38:41], v[110:113], v[174:177], v[38:41]
	v_mfma_f32_16x16x32_bf16 v[42:45], v[118:121], v[150:153], v[42:45]
	v_mfma_f32_16x16x32_bf16 v[50:53], v[118:121], v[158:161], v[50:53]
	v_mfma_f32_16x16x32_bf16 v[46:49], v[118:121], v[166:169], v[46:49]
	v_mfma_f32_16x16x32_bf16 v[58:61], v[118:121], v[174:177], v[58:61]
	v_mfma_f32_16x16x32_bf16 v[54:57], v[126:129], v[150:153], v[54:57]
	v_mfma_f32_16x16x32_bf16 v[66:69], v[126:129], v[158:161], v[66:69]
	v_mfma_f32_16x16x32_bf16 v[62:65], v[126:129], v[166:169], v[62:65]
	v_mfma_f32_16x16x32_bf16 v[70:73], v[126:129], v[174:177], v[70:73]
	v_mfma_f32_16x16x32_bf16 v[10:13], v[106:109], v[154:157], v[10:13]
	v_mfma_f32_16x16x32_bf16 v[14:17], v[106:109], v[162:165], v[14:17]
	v_mfma_f32_16x16x32_bf16 v[18:21], v[106:109], v[170:173], v[18:21]
	v_mfma_f32_16x16x32_bf16 v[22:25], v[106:109], v[178:181], v[22:25]
	v_mfma_f32_16x16x32_bf16 v[26:29], v[114:117], v[154:157], v[26:29]
	v_mfma_f32_16x16x32_bf16 v[34:37], v[114:117], v[162:165], v[34:37]
	v_mfma_f32_16x16x32_bf16 v[30:33], v[114:117], v[170:173], v[30:33]
	v_mfma_f32_16x16x32_bf16 v[38:41], v[114:117], v[178:181], v[38:41]
	v_mfma_f32_16x16x32_bf16 v[42:45], v[122:125], v[154:157], v[42:45]
	v_mfma_f32_16x16x32_bf16 v[50:53], v[122:125], v[162:165], v[50:53]
	v_mfma_f32_16x16x32_bf16 v[46:49], v[122:125], v[170:173], v[46:49]
	v_mfma_f32_16x16x32_bf16 v[58:61], v[122:125], v[178:181], v[58:61]
	v_mfma_f32_16x16x32_bf16 v[54:57], v[130:133], v[154:157], v[54:57]
	v_mfma_f32_16x16x32_bf16 v[66:69], v[130:133], v[162:165], v[66:69]
	v_mfma_f32_16x16x32_bf16 v[62:65], v[130:133], v[170:173], v[62:65]
	v_mfma_f32_16x16x32_bf16 v[70:73], v[130:133], v[178:181], v[70:73]
	v_add_u32_e32 v0, 0x1000, v93
	s_barrier
; template <bool GATE>
; __device__ __forceinline__ void sample_gemm_res(LAS unsigned char* lds, const bf16* Amat, const bf16* Bt, const bf16* Hin, bf16* Hout, float* rss_out, const bf16* PP, const float* rss_in, int bid, int tid) {
;     ...
; #pragma unroll
;     for (int mi = 0; mi < 4; ++mi)
; #pragma unroll
;         for (int ni = 0; ni < 4; ++ni)
; #pragma unroll
;             for (int i = 0; i < 4; ++i) red[(wave * 64 + 16 * mi + kg * 4 + i) * 65 + 16 * ni + lr] = acc[mi][ni][i];
;     __syncthreads();
	ds_write2_b32 v93, v10, v14 offset1:16
	ds_write2_b32 v93, v11, v15 offset0:65 offset1:81
	ds_write2_b32 v93, v12, v16 offset0:130 offset1:146
	ds_write2_b32 v93, v13, v17 offset0:195 offset1:211
	ds_write2_b32 v93, v18, v22 offset0:32 offset1:48
	ds_write2_b32 v93, v19, v23 offset0:97 offset1:113
	ds_write2_b32 v93, v20, v24 offset0:162 offset1:178
	ds_write2_b32 v93, v21, v25 offset0:227 offset1:243
	ds_write2_b32 v0, v26, v34 offset0:16 offset1:32
	ds_write2_b32 v0, v27, v35 offset0:81 offset1:97
	ds_write2_b32 v0, v28, v36 offset0:146 offset1:162
	ds_write2_b32 v0, v29, v37 offset0:211 offset1:227
	ds_write2_b32 v0, v30, v38 offset0:48 offset1:64
	ds_write2_b32 v0, v31, v39 offset0:113 offset1:129
	ds_write2_b32 v0, v32, v40 offset0:178 offset1:194
	v_add_u32_e32 v0, 0x1200, v93
	ds_write2_b32 v0, v33, v41 offset0:115 offset1:131
	v_add_u32_e32 v0, 0x2000, v93
	ds_write2_b32 v0, v42, v50 offset0:32 offset1:48
	ds_write2_b32 v0, v43, v51 offset0:97 offset1:113
	ds_write2_b32 v0, v44, v52 offset0:162 offset1:178
	ds_write2_b32 v0, v45, v53 offset0:227 offset1:243
	ds_write2_b32 v0, v46, v58 offset0:64 offset1:80
	ds_write2_b32 v0, v47, v59 offset0:129 offset1:145
	ds_write2_b32 v0, v48, v60 offset0:194 offset1:210
	v_add_u32_e32 v0, 0x2400, v93
	ds_write2_b32 v0, v49, v61 offset0:3 offset1:19
	v_add_u32_e32 v0, 0x3000, v93
	v_add_u32_e32 v10, 0x3200, v93
	ds_write2_b32 v0, v54, v66 offset0:48 offset1:64
	ds_write2_b32 v0, v55, v67 offset0:113 offset1:129
	ds_write2_b32 v0, v56, v68 offset0:178 offset1:194
	ds_write2_b32 v10, v57, v69 offset0:115 offset1:131
	ds_write2_b32 v0, v62, v70 offset0:80 offset1:96
	ds_write2_b32 v0, v63, v71 offset0:145 offset1:161
	ds_write2_b32 v0, v64, v72 offset0:210 offset1:226
	v_add_u32_e32 v0, 0x3400, v93
	ds_write2_b32 v0, v65, v73 offset0:19 offset1:35
	v_add_u32_e32 v0, v89, v94
	s_waitcnt lgkmcnt(0)
	s_barrier
; __device__ __forceinline__ unsigned cvtpk(float lo, float hi) { f32x2_t v = {lo, hi}; bf16x2_t b = __builtin_convertvector(v, bf16x2_t); return __builtin_bit_cast(unsigned, b); }
; template <bool GATE>
; __device__ __forceinline__ void sample_gemm_res(LAS unsigned char* lds, const bf16* Amat, const bf16* Bt, const bf16* Hin, bf16* Hout, float* rss_out, const bf16* PP, const float* rss_in, int bid, int tid) {
;     ...
;     { const int row = tid >> 3, c8 = (tid & 7) * 8, grow = m0 + row; float v[8];
; #pragma unroll
;       for (int e = 0; e < 8; ++e) { float sacc = 0.f;
; #pragma unroll
;           for (int w = 0; w < 8; ++w) sacc += red[(w * 64 + row) * 65 + c8 + e];
;           v[e] = sacc; }
;       float sc = 1.f; if (GATE) sc = rsqrtf(rsi * (1.f / 2048.f) + 1e-6f);
;       const size_t p = (size_t)grow * 2048 + n0 + c8;
;       const unsigned hws[4] = {hw.x, hw.y, hw.z, hw.w}, pws[4] = {pw.x, pw.y, pw.z, pw.w}; unsigned ow[4]; float sq = 0.f;
; #pragma unroll
;       for (int e2 = 0; e2 < 4; ++e2) { float h0 = __uint_as_float(hws[e2] << 16), h1 = __uint_as_float(hws[e2] & 0xffff0000u);
;           if (GATE) { h0 += __builtin_amdgcn_rcpf(1.f + __expf(-sc * v[2 * e2])) * __uint_as_float(pws[e2] << 16); h1 += __builtin_amdgcn_rcpf(1.f + __expf(-sc * v[2 * e2 + 1])) * __uint_as_float(pws[e2] & 0xffff0000u); }
;           else { h0 += v[2 * e2]; h1 += v[2 * e2 + 1]; }
;           sq += h0 * h0 + h1 * h1; ow[e2] = cvtpk(h0, h1); }
;       *(u32x4*)(Hout + p) = (u32x4){ow[0], ow[1], ow[2], ow[3]};
;       sq += __shfl_xor(sq, 1); sq += __shfl_xor(sq, 2); sq += __shfl_xor(sq, 4);
;       if ((tid & 7) == 0) atomicAdd(rss_out + grow, sq); }
;     __syncthreads();
	ds_read2_b32 v[10:11], v0 offset1:1
	v_add_u32_e32 v12, 0x4100, v0
	v_add_u32_e32 v14, 0x8200, v0
	v_add_u32_e32 v16, 0xc300, v0
	ds_read2_b32 v[12:13], v12 offset1:1
	ds_read2_b32 v[14:15], v14 offset1:1
	ds_read2_b32 v[16:17], v16 offset1:1
	ds_read2_b32 v[18:19], v0 offset0:2 offset1:3
	ds_read2_b32 v[20:21], v0 offset0:4 offset1:5
	ds_read2_b32 v[22:23], v0 offset0:6 offset1:7
	ds_read2_b32 v[24:25], v96 offset1:1
	ds_read2_b32 v[26:27], v97 offset1:1
	s_waitcnt lgkmcnt(8)
	v_add_f32_e32 v10, 0, v10
	s_waitcnt lgkmcnt(7)
	v_add_f32_e32 v10, v10, v12
	s_waitcnt lgkmcnt(6)
	v_add_f32_e32 v10, v10, v14
	s_waitcnt lgkmcnt(5)
	v_add_f32_e32 v10, v10, v16
	s_waitcnt lgkmcnt(1)
	v_add_f32_e32 v10, v10, v24
	ds_read2_b32 v[28:29], v96 offset0:2 offset1:3
	ds_read2_b32 v[30:31], v96 offset0:4 offset1:5
	ds_read2_b32 v[32:33], v96 offset0:6 offset1:7
	s_waitcnt lgkmcnt(3)
	v_add_f32_e32 v10, v10, v26
	ds_read2_b32 v[34:35], v98 offset1:1
	ds_read2_b32 v[36:37], v99 offset1:1
	ds_read2_b32 v[38:39], v97 offset0:2 offset1:3
	ds_read2_b32 v[40:41], v97 offset0:4 offset1:5
	ds_read2_b32 v[42:43], v97 offset0:6 offset1:7
	s_waitcnt lgkmcnt(4)
	v_add_f32_e32 v10, v10, v34
	s_waitcnt lgkmcnt(3)
	v_add_f32_e32 v50, v10, v36
	v_add_f32_e32 v10, 0, v11
	v_add_f32_e32 v10, v10, v13
	v_add_f32_e32 v10, v10, v15
	v_add_f32_e32 v10, v10, v17
	v_add_f32_e32 v10, v10, v25
	v_add_f32_e32 v10, v10, v27
	v_add_f32_e32 v10, v10, v35
	v_add_f32_e32 v51, v10, v37
	v_add_u32_e32 v10, 0x4108, v0
	ds_read2_b32 v[44:45], v98 offset0:2 offset1:3
	ds_read2_b32 v[46:47], v98 offset0:4 offset1:5
	ds_read2_b32 v[48:49], v98 offset0:6 offset1:7
	ds_read2_b32 v[10:11], v10 offset1:1
	v_add_f32_e32 v18, 0, v18
	v_add_u32_e32 v26, 0xc308, v0
	ds_read2_b32 v[12:13], v99 offset0:2 offset1:3
	ds_read2_b32 v[14:15], v99 offset0:4 offset1:5
	ds_read2_b32 v[16:17], v99 offset0:6 offset1:7
	v_add_u32_e32 v36, 0x8210, v0
	s_waitcnt lgkmcnt(3)
	v_add_f32_e32 v10, v18, v10
	v_add_u32_e32 v18, 0x8208, v0
	ds_read2_b32 v[24:25], v18 offset1:1
	ds_read2_b32 v[26:27], v26 offset1:1
	v_add_u32_e32 v18, 0x4110, v0
	ds_read2_b32 v[34:35], v18 offset1:1
	ds_read2_b32 v[36:37], v36 offset1:1
	v_add_u32_e32 v18, 0x8218, v0
	s_waitcnt lgkmcnt(3)
	v_add_f32_e32 v10, v10, v24
	s_waitcnt lgkmcnt(2)
	v_add_f32_e32 v10, v10, v26
	v_add_f32_e32 v10, v10, v28
	v_add_f32_e32 v10, v10, v38
	v_add_f32_e32 v10, v10, v44
	v_add_f32_e32 v26, v10, v12
	v_add_f32_e32 v10, 0, v19
	v_add_f32_e32 v10, v10, v11
	v_add_f32_e32 v10, v10, v25
	v_add_f32_e32 v10, v10, v27
	v_add_f32_e32 v10, v10, v29
	v_add_f32_e32 v10, v10, v39
	v_add_f32_e32 v10, v10, v45
	v_add_f32_e32 v27, v10, v13
	v_add_f32_e32 v10, 0, v20
	s_waitcnt lgkmcnt(1)
	v_add_f32_e32 v10, v10, v34
	s_waitcnt lgkmcnt(0)
	v_add_f32_e32 v20, v10, v36
	v_add_u32_e32 v10, 0xc310, v0
	ds_read2_b32 v[10:11], v10 offset1:1
	v_add_u32_e32 v12, 0x4118, v0
	v_add_u32_e32 v0, 0xc318, v0
	ds_read2_b32 v[12:13], v12 offset1:1
	ds_read2_b32 v[18:19], v18 offset1:1
	ds_read2_b32 v[24:25], v0 offset1:1
	s_waitcnt lgkmcnt(3)
	v_add_f32_e32 v0, v20, v10
	v_add_f32_e32 v10, 0, v21
	v_add_f32_e32 v10, v10, v35
	v_add_f32_e32 v10, v10, v37
	v_add_f32_e32 v10, v10, v11
	v_add_f32_e32 v10, v10, v31
	v_add_f32_e32 v10, v10, v41
	v_add_f32_e32 v10, v10, v47
	v_add_f32_e32 v20, v10, v15
	v_add_f32_e32 v10, 0, v22
	v_fmamk_f32 v11, v100, 0x3a000000, v214
	s_waitcnt lgkmcnt(2)
	v_add_f32_e32 v10, v10, v12
	v_mul_f32_e32 v12, 0x4b800000, v11
	v_cmp_gt_f32_e64 s[40:41], s65, v11
	s_waitcnt lgkmcnt(1)
	v_add_f32_e32 v10, v10, v18
	s_waitcnt lgkmcnt(0)
	v_add_f32_e32 v10, v10, v24
	v_cndmask_b32_e64 v11, v11, v12, s[40:41]
	v_rsq_f32_e32 v11, v11
	v_add_f32_e32 v10, v10, v32
	v_add_f32_e32 v10, v10, v42
	v_add_f32_e32 v10, v10, v48
	v_mul_f32_e32 v12, 0x45800000, v11
	v_add_f32_e32 v21, v10, v16
	v_add_f32_e32 v10, 0, v23
	v_cndmask_b32_e64 v22, v11, v12, s[40:41]
	v_add_f32_e32 v10, v10, v13
	v_mul_f32_e64 v11, v50, -v22
	v_mul_f32_e64 v12, v51, -v22
	v_add_f32_e32 v10, v10, v19
	v_mul_f32_e32 v11, 0x3fb8aa3b, v11
	v_mul_f32_e32 v12, 0x3fb8aa3b, v12
	v_add_f32_e32 v0, v0, v30
	v_add_f32_e32 v10, v10, v25
	v_exp_f32_e32 v11, v11
	v_exp_f32_e32 v12, v12
	v_add_f32_e32 v0, v0, v40
	v_add_f32_e32 v10, v10, v33
	v_add_f32_e32 v0, v0, v46
	v_add_f32_e32 v10, v10, v43
	v_add_f32_e32 v0, v0, v14
	v_add_f32_e32 v10, v10, v49
	v_lshlrev_b32_e32 v14, 16, v2
	v_and_b32_e32 v15, 0xffff0000, v2
	v_mul_f32_e64 v2, v26, -v22
	v_add_f32_e32 v23, v10, v17
	v_add_f32_e32 v10, 1.0, v11
	v_add_f32_e32 v11, 1.0, v12
	v_lshlrev_b32_e32 v12, 16, v6
	v_and_b32_e32 v13, 0xffff0000, v6
	v_mul_f32_e32 v2, 0x3fb8aa3b, v2
	v_mul_f32_e64 v6, v27, -v22
	v_exp_f32_e32 v2, v2
	v_mul_f32_e32 v6, 0x3fb8aa3b, v6
	v_rcp_f32_e32 v10, v10
	v_rcp_f32_e32 v11, v11
	v_exp_f32_e32 v6, v6
	v_add_f32_e32 v2, 1.0, v2
	v_mul_f32_e64 v0, v0, -v22
	v_pk_fma_f32 v[10:11], v[10:11], v[14:15], v[12:13]
	v_rcp_f32_e32 v14, v2
	v_add_f32_e32 v2, 1.0, v6
	v_rcp_f32_e32 v15, v2
	v_lshlrev_b32_e32 v6, 16, v7
	v_and_b32_e32 v7, 0xffff0000, v7
	v_lshlrev_b32_e32 v2, 16, v3
	v_and_b32_e32 v3, 0xffff0000, v3
	v_pk_fma_f32 v[2:3], v[14:15], v[2:3], v[6:7]
	v_mul_f32_e32 v0, 0x3fb8aa3b, v0
	v_mul_f32_e64 v6, v20, -v22
	v_exp_f32_e32 v0, v0
	v_mul_f32_e32 v6, 0x3fb8aa3b, v6
	v_exp_f32_e32 v15, v6
	v_lshlrev_b32_e32 v18, 16, v4
	v_add_f32_e32 v0, 1.0, v0
	v_rcp_f32_e32 v14, v0
	v_add_f32_e32 v0, 1.0, v15
	v_rcp_f32_e32 v15, v0
	v_mul_f32_e64 v0, v21, -v22
	v_and_b32_e32 v19, 0xffff0000, v4
	v_mul_f32_e32 v0, 0x3fb8aa3b, v0
	v_mul_f32_e64 v4, v23, -v22
	v_exp_f32_e32 v0, v0
	v_mul_f32_e32 v4, 0x3fb8aa3b, v4
	v_exp_f32_e32 v4, v4
	v_lshlrev_b32_e32 v16, 16, v8
	v_and_b32_e32 v17, 0xffff0000, v8
	v_add_f32_e32 v0, 1.0, v0
	v_pk_fma_f32 v[14:15], v[14:15], v[18:19], v[16:17]
	v_rcp_f32_e32 v18, v0
	v_add_f32_e32 v0, 1.0, v4
	v_rcp_f32_e32 v19, v0
	v_pk_mul_f32 v[12:13], v[10:11], v[10:11]
	v_pk_mul_f32 v[6:7], v[2:3], v[2:3]
	v_lshlrev_b32_e32 v8, 16, v9
	v_and_b32_e32 v9, 0xffff0000, v9
	v_lshlrev_b32_e32 v4, 16, v5
	v_and_b32_e32 v5, 0xffff0000, v5
	v_pk_mul_f32 v[16:17], v[14:15], v[14:15]
	v_pk_fma_f32 v[8:9], v[18:19], v[4:5], v[8:9]
	v_add_f32_e32 v0, v6, v7
	v_add_f32_e32 v6, v12, v13
	v_pk_mul_f32 v[4:5], v[8:9], v[8:9]
	v_add_f32_e32 v0, v6, v0
	v_add_f32_e32 v6, v16, v17
	v_add_f32_e32 v0, v0, v6
	v_add_f32_e32 v4, v4, v5
	v_add_f32_e32 v0, v0, v4
	ds_bpermute_b32 v4, v90, v0
	v_cvt_pk_bf16_f32 v5, v2, v3
	v_cvt_pk_bf16_f32 v7, v8, v9
	v_lshl_add_u64 v[8:9], v[82:83], 1, s[48:49]
	s_waitcnt lgkmcnt(0)
	v_add_f32_e32 v0, v0, v4
	ds_bpermute_b32 v6, v91, v0
	v_cvt_pk_bf16_f32 v4, v10, v11
	s_waitcnt lgkmcnt(0)
	v_add_f32_e32 v0, v0, v6
	ds_bpermute_b32 v2, v92, v0
	v_cvt_pk_bf16_f32 v6, v14, v15
	global_store_dwordx4 v[8:9], v[4:7], off
	s_and_saveexec_b64 s[0:1], vcc
	s_cbranch_execz .LBB0_66
	s_waitcnt lgkmcnt(0)
	v_add_f32_e32 v0, v0, v2
	v_lshl_add_u64 v[2:3], v[80:81], 2, s[50:51]
	global_atomic_add_f32 v[2:3], v0, off
	s_branch .LBB0_66

; #define LAS __attribute__((address_space(3)))
; template <bool GATE>
; __device__ __forceinline__ void sample_gemm_res(LAS unsigned char* lds, const bf16* Amat, const bf16* Bt, const bf16* Hin, bf16* Hout, float* rss_out, const bf16* PP, const float* rss_in, int bid, int tid) {
;     const int wave = tid >> 6, lane = tid & 63, lr = lane & 15, kg = lane >> 4;
;   for (int tile = bid; tile < 256; tile += (int)gridDim.x) {
;     const int m0 = TP + (tile & 7) * 64, n0 = (tile >> 3) * 64;
;     const bf16x8* ap = (const bf16x8*)(Amat + (size_t)(m0 + lr) * 2048 + wave * 256 + 8 * kg);
;     const bf16x8* bp = (const bf16x8*)(Bt + (size_t)(n0 + lr) * 2048 + wave * 256 + 8 * kg);
;     const int erow = m0 + (tid >> 3); const size_t ep = (size_t)erow * 2048 + n0 + (tid & 7) * 8;
.LBB0_112:
	v_mov_b32_e32 v0, v183
	s_and_b64 vcc, exec, s[40:41]
	s_cbranch_vccnz .LBB0_119
	v_and_b32_e32 v8, 64, v216
	v_xor_b32_e32 v7, 1, v216
	v_add_u32_e32 v8, 64, v8
	v_cmp_lt_i32_e32 vcc, v7, v8
	s_waitcnt vmcnt(0)
	v_and_b32_e32 v71, 15, v0
	v_bfe_u32 v4, v0, 4, 2
	v_cndmask_b32_e32 v7, v216, v7, vcc
	v_lshlrev_b32_e32 v86, 2, v7
	v_xor_b32_e32 v7, 2, v216
	v_lshlrev_b32_e32 v2, 2, v0
	v_ashrrev_i32_e32 v84, 3, v0
	v_and_b32_e32 v5, 7, v0
	v_and_b32_e32 v0, 0x3fffffc0, v0
	v_cmp_lt_i32_e32 vcc, v7, v8
	v_lshl_or_b32 v0, v4, 2, v0
	v_lshlrev_b32_e32 v6, 2, v71
	v_cndmask_b32_e32 v7, v216, v7, vcc
	v_lshlrev_b32_e32 v87, 2, v7
	v_xor_b32_e32 v7, 4, v216
	v_mul_lo_u32 v0, v0, s30
	s_add_u32 s0, s14, s52
	v_cmp_lt_i32_e32 vcc, v7, v8
	v_add3_u32 v89, 0, v6, v0
	s_addc_u32 s1, 0, s53
	v_lshlrev_b32_e32 v0, 4, v4
	v_lshlrev_b32_e32 v70, 3, v5
	v_lshl_add_u32 v85, v5, 5, 0
	v_cndmask_b32_e32 v7, v216, v7, vcc
	v_cmp_eq_u32_e32 vcc, 0, v5
	v_lshl_add_u64 v[4:5], s[0:1], 0, v[0:1]
	s_load_dwordx2 s[0:1], s[60:61], 0x148
	v_and_b32_e32 v2, 0xffffff00, v2
	s_waitcnt lgkmcnt(0)
	v_ashrrev_i32_e32 v3, 31, v2
	v_mul_lo_u32 v90, v84, s30
	v_lshlrev_b64 v[2:3], 1, v[2:3]
	v_lshlrev_b32_e32 v88, 2, v7
	v_add_u32_e32 v6, 0x10400, v90
	v_add_u32_e32 v7, 0x14500, v90
	v_add_u32_e32 v8, 0x18600, v90
	v_add_u32_e32 v9, 0x1c700, v90
	v_lshl_add_u64 v[4:5], v[4:5], 0, v[2:3]
	v_or_b32_e32 v2, v2, v0
	v_readlane_b32 s6, v254, 39
	v_lshl_add_u64 v[72:73], s[0:1], 0, v[4:5]
	v_lshl_add_u64 v[74:75], s[0:1], 0, v[2:3]
	v_or_b32_e32 v91, 0x2000, v71
	s_lshl_b32 s2, s6, 6
	v_add_u32_e32 v92, v85, v6
	v_add_u32_e32 v93, v85, v7
	v_add_u32_e32 v94, v85, v8
	v_add_u32_e32 v95, v85, v9
	s_and_b32 s4, s6, 7
	s_lshr_b32 s5, s6, 3
	s_lshl_b32 s4, s4, 2
	s_lshr_b32 s2, s5, 3
	s_add_i32 s4, s4, s2
	s_and_b32 s5, s5, 7
	s_lshl_b32 s4, s4, 3
	s_or_b32 s6, s4, s5
	s_lshl_b32 s2, s6, 6
	s_lshl_b32 s3, s6, 3
	s_branch .LBB0_115

; template <bool GATE>
; __device__ __forceinline__ void sample_gemm_res(LAS unsigned char* lds, const bf16* Amat, const bf16* Bt, const bf16* Hin, bf16* Hout, float* rss_out, const bf16* PP, const float* rss_in, int bid, int tid) {
;     ...
;   for (int tile = bid; tile < 256; tile += (int)gridDim.x) {
;     const int m0 = TP + (tile & 7) * 64, n0 = (tile >> 3) * 64;
;     const bf16x8* ap = (const bf16x8*)(Amat + (size_t)(m0 + lr) * 2048 + wave * 256 + 8 * kg);
;     const bf16x8* bp = (const bf16x8*)(Bt + (size_t)(n0 + lr) * 2048 + wave * 256 + 8 * kg);
;     const int erow = m0 + (tid >> 3); const size_t ep = (size_t)erow * 2048 + n0 + (tid & 7) * 8;
;     const u32x4 hw = *(const u32x4*)(Hin + ep); u32x4 pw = (u32x4){0u, 0u, 0u, 0u}; float rsi = 0.f; if (GATE) { pw = *(const u32x4*)(PP + ep); rsi = rss_in[erow]; }
;     f32x4m acc[4][4];
; #pragma unroll
;     for (int mi = 0; mi < 4; ++mi)
; #pragma unroll
;         for (int ni = 0; ni < 4; ++ni) acc[mi][ni] = (f32x4m){0.f, 0.f, 0.f, 0.f};
; #pragma unroll 2
;     for (int ks = 0; ks < 8; ++ks) { bf16x8 a[4], b[4];
; #pragma unroll
;         for (int q = 0; q < 4; ++q) { a[q] = ap[(size_t)q * 16 * 256 + ks * 4]; b[q] = bp[(size_t)q * 16 * 256 + ks * 4]; }
; #pragma unroll
;         for (int mi = 0; mi < 4; ++mi)
; #pragma unroll
;             for (int ni = 0; ni < 4; ++ni) acc[mi][ni] = __builtin_amdgcn_mfma_f32_16x16x32_bf16(a[mi], b[ni], acc[mi][ni], 0, 0, 0); }
.LBB0_115:
	s_lshl_b32 s0, s6, 6
	s_and_b32 s1, s0, 0x1c0
	v_add_u32_e32 v0, s1, v84
	s_lshl_b32 s0, s6, 3
	v_add_u32_e32 v76, 0x2000, v0
	s_andn2_b32 s0, s0, 63
	v_ashrrev_i32_e32 v77, 31, v76
	v_lshlrev_b64 v[2:3], 11, v[76:77]
	s_ashr_i32 s1, s0, 31
	v_lshl_add_u64 v[78:79], v[2:3], 0, s[0:1]
	v_or_b32_e32 v78, v78, v70
	v_lshl_add_u64 v[2:3], v[78:79], 1, s[46:47]
	global_load_dwordx4 v[2:5], v[2:3], off
	s_and_b32 s0, s3, 0xffffffc0
	v_or_b32_e32 v6, s0, v71
	v_ashrrev_i32_e32 v7, 31, v6
	v_lshlrev_b64 v[6:7], 12, v[6:7]
	s_and_b32 s0, s2, 0x1c0
	v_lshl_add_u64 v[80:81], v[72:73], 0, v[6:7]
	v_add_lshl_u32 v0, v91, s0, 12
	v_mov_b32_e32 v6, 0
	v_lshl_add_u64 v[82:83], v[74:75], 0, v[0:1]
	s_mov_b64 s[4:5], 0
	v_mov_b32_e32 v7, v6
	v_mov_b32_e32 v8, v6
	v_mov_b32_e32 v9, v6
	v_mov_b32_e32 v10, v6
	v_mov_b32_e32 v11, v6
	v_mov_b32_e32 v12, v6
	v_mov_b32_e32 v13, v6
	v_mov_b32_e32 v14, v6
	v_mov_b32_e32 v15, v6
	v_mov_b32_e32 v16, v6
	v_mov_b32_e32 v17, v6
	v_mov_b32_e32 v18, v6
	v_mov_b32_e32 v19, v6
	v_mov_b32_e32 v20, v6
	v_mov_b32_e32 v21, v6
	v_mov_b32_e32 v22, v6
	v_mov_b32_e32 v23, v6
	v_mov_b32_e32 v24, v6
	v_mov_b32_e32 v25, v6
	v_mov_b32_e32 v30, v6
	v_mov_b32_e32 v31, v6
	v_mov_b32_e32 v32, v6
	v_mov_b32_e32 v33, v6
	v_mov_b32_e32 v26, v6
	v_mov_b32_e32 v27, v6
	v_mov_b32_e32 v28, v6
	v_mov_b32_e32 v29, v6
	v_mov_b32_e32 v34, v6
	v_mov_b32_e32 v35, v6
	v_mov_b32_e32 v36, v6
	v_mov_b32_e32 v37, v6
	v_mov_b32_e32 v38, v6
	v_mov_b32_e32 v39, v6
	v_mov_b32_e32 v40, v6
	v_mov_b32_e32 v41, v6
	v_mov_b32_e32 v46, v6
	v_mov_b32_e32 v47, v6
	v_mov_b32_e32 v48, v6
	v_mov_b32_e32 v49, v6
	v_mov_b32_e32 v42, v6
	v_mov_b32_e32 v43, v6
	v_mov_b32_e32 v44, v6
	v_mov_b32_e32 v45, v6
	v_mov_b32_e32 v54, v6
	v_mov_b32_e32 v55, v6
	v_mov_b32_e32 v56, v6
	v_mov_b32_e32 v57, v6
	v_mov_b32_e32 v50, v6
	v_mov_b32_e32 v51, v6
	v_mov_b32_e32 v52, v6
	v_mov_b32_e32 v53, v6
	v_mov_b32_e32 v62, v6
	v_mov_b32_e32 v63, v6
	v_mov_b32_e32 v64, v6
	v_mov_b32_e32 v65, v6
	v_mov_b32_e32 v58, v6
	v_mov_b32_e32 v59, v6
	v_mov_b32_e32 v60, v6
	v_mov_b32_e32 v61, v6
	v_mov_b32_e32 v66, v6
	v_mov_b32_e32 v67, v6
	v_mov_b32_e32 v68, v6
	v_mov_b32_e32 v69, v6
	s_mov_b32 s1, 0x10000
	v_readfirstlane_b32 s8, v82
	v_readfirstlane_b32 s9, v83
	v_readfirstlane_b32 s10, v80
	v_readfirstlane_b32 s11, v81
	s_add_u32 s8, s8, 0x10c00000
	s_addc_u32 s9, s9, 0
	s_add_u32 s10, s10, 0x0
	s_addc_u32 s11, s11, 0
	v_lshrrev_b32_e32 v212, 3, v216
	v_and_b32_e32 v213, 7, v216
	v_xor_b32_e32 v213, v213, v212
	v_lshlrev_b32_e32 v213, 4, v213
	v_lshl_or_b32 v248, v212, 12, v213
	v_and_b32_e32 v212, 15, v216
	v_lshrrev_b32_e32 v213, 4, v216
	v_and_b32_e32 v249, 7, v212
	v_xor_b32_e32 v213, v213, v249
	v_lshlrev_b32_e32 v213, 4, v213
	v_lshl_or_b32 v249, v212, 7, v213
	v_lshrrev_b32_e32 v212, 6, v183
	s_nop 0
	v_readfirstlane_b32 s7, v212
	s_lshl_b32 s7, s7, 14
	v_add_u32_e32 v249, s7, v249
	v_xor_b32_e32 v250, 64, v249
	s_add_i32 m0, s7, 0x0
	s_add_u32 s4, s8, 0x0
	s_addc_u32 s5, s9, 0
	global_load_lds_dwordx4 v248, s[4:5]
	s_add_i32 m0, s7, 0x400
	s_add_u32 s4, s8, 0x8000
	s_addc_u32 s5, s9, 0
	global_load_lds_dwordx4 v248, s[4:5]
	s_add_i32 m0, s7, 0x800
	s_add_u32 s4, s8, 0x10000
	s_addc_u32 s5, s9, 0
	global_load_lds_dwordx4 v248, s[4:5]
	s_add_i32 m0, s7, 0xc00
	s_add_u32 s4, s8, 0x18000
	s_addc_u32 s5, s9, 0
	global_load_lds_dwordx4 v248, s[4:5]
	s_add_i32 m0, s7, 0x1000
	s_add_u32 s4, s8, 0x20000
	s_addc_u32 s5, s9, 0
	global_load_lds_dwordx4 v248, s[4:5]
	s_add_i32 m0, s7, 0x1400
	s_add_u32 s4, s8, 0x28000
	s_addc_u32 s5, s9, 0
	global_load_lds_dwordx4 v248, s[4:5]
	s_add_i32 m0, s7, 0x1800
	s_add_u32 s4, s8, 0x30000
	s_addc_u32 s5, s9, 0
	global_load_lds_dwordx4 v248, s[4:5]
	s_add_i32 m0, s7, 0x1c00
	s_add_u32 s4, s8, 0x38000
	s_addc_u32 s5, s9, 0
	global_load_lds_dwordx4 v248, s[4:5]
	s_add_i32 m0, s7, 0x2000
	s_add_u32 s4, s10, 0x0
	s_addc_u32 s5, s11, 0
	global_load_lds_dwordx4 v248, s[4:5]
	s_add_i32 m0, s7, 0x2400
	s_add_u32 s4, s10, 0x8000
	s_addc_u32 s5, s11, 0
	global_load_lds_dwordx4 v248, s[4:5]
	s_add_i32 m0, s7, 0x2800
	s_add_u32 s4, s10, 0x10000
	s_addc_u32 s5, s11, 0
	global_load_lds_dwordx4 v248, s[4:5]
	s_add_i32 m0, s7, 0x2c00
	s_add_u32 s4, s10, 0x18000
	s_addc_u32 s5, s11, 0
	global_load_lds_dwordx4 v248, s[4:5]
	s_add_i32 m0, s7, 0x3000
	s_add_u32 s4, s10, 0x20000
	s_addc_u32 s5, s11, 0
	global_load_lds_dwordx4 v248, s[4:5]
	s_add_i32 m0, s7, 0x3400
	s_add_u32 s4, s10, 0x28000
	s_addc_u32 s5, s11, 0
	global_load_lds_dwordx4 v248, s[4:5]
	s_add_i32 m0, s7, 0x3800
	s_add_u32 s4, s10, 0x30000
	s_addc_u32 s5, s11, 0
	global_load_lds_dwordx4 v248, s[4:5]
	s_add_i32 m0, s7, 0x3c00
	s_add_u32 s4, s10, 0x38000
	s_addc_u32 s5, s11, 0
	global_load_lds_dwordx4 v248, s[4:5]
	s_waitcnt vmcnt(0)
	ds_read_b128 v[96:99], v249 offset:0
	ds_read_b128 v[100:103], v250 offset:0
	ds_read_b128 v[104:107], v249 offset:2048
	ds_read_b128 v[108:111], v250 offset:2048
	ds_read_b128 v[112:115], v249 offset:4096
	ds_read_b128 v[116:119], v250 offset:4096
	ds_read_b128 v[120:123], v249 offset:6144
	ds_read_b128 v[124:127], v250 offset:6144
	ds_read_b128 v[144:147], v249 offset:8192
	ds_read_b128 v[148:151], v250 offset:8192
	ds_read_b128 v[152:155], v249 offset:10240
	ds_read_b128 v[156:159], v250 offset:10240
	ds_read_b128 v[160:163], v249 offset:12288
	ds_read_b128 v[164:167], v250 offset:12288
	ds_read_b128 v[168:171], v249 offset:14336
	ds_read_b128 v[172:175], v250 offset:14336
	s_waitcnt lgkmcnt(0)
; template <bool GATE>
; __device__ __forceinline__ void sample_gemm_res(LAS unsigned char* lds, const bf16* Amat, const bf16* Bt, const bf16* Hin, bf16* Hout, float* rss_out, const bf16* PP, const float* rss_in, int bid, int tid) {
;     ...
;     for (int ks = 0; ks < 8; ++ks) { bf16x8 a[4], b[4];
; #pragma unroll
;         for (int q = 0; q < 4; ++q) { a[q] = ap[(size_t)q * 16 * 256 + ks * 4]; b[q] = bp[(size_t)q * 16 * 256 + ks * 4]; }
; #pragma unroll
;         for (int mi = 0; mi < 4; ++mi)
; #pragma unroll
;             for (int ni = 0; ni < 4; ++ni) acc[mi][ni] = __builtin_amdgcn_mfma_f32_16x16x32_bf16(a[mi], b[ni], acc[mi][ni], 0, 0, 0); }
	s_add_i32 m0, s7, 0x0
	s_add_u32 s4, s8, 0x80
	s_addc_u32 s5, s9, 0
	global_load_lds_dwordx4 v248, s[4:5]
	s_add_i32 m0, s7, 0x400
	s_add_u32 s4, s8, 0x8080
	s_addc_u32 s5, s9, 0
	global_load_lds_dwordx4 v248, s[4:5]
	s_add_i32 m0, s7, 0x800
	s_add_u32 s4, s8, 0x10080
	s_addc_u32 s5, s9, 0
	global_load_lds_dwordx4 v248, s[4:5]
	s_add_i32 m0, s7, 0xc00
	s_add_u32 s4, s8, 0x18080
	s_addc_u32 s5, s9, 0
	global_load_lds_dwordx4 v248, s[4:5]
	s_add_i32 m0, s7, 0x1000
	s_add_u32 s4, s8, 0x20080
	s_addc_u32 s5, s9, 0
	global_load_lds_dwordx4 v248, s[4:5]
	s_add_i32 m0, s7, 0x1400
	s_add_u32 s4, s8, 0x28080
	s_addc_u32 s5, s9, 0
	global_load_lds_dwordx4 v248, s[4:5]
	s_add_i32 m0, s7, 0x1800
	s_add_u32 s4, s8, 0x30080
	s_addc_u32 s5, s9, 0
	global_load_lds_dwordx4 v248, s[4:5]
	s_add_i32 m0, s7, 0x1c00
	s_add_u32 s4, s8, 0x38080
	s_addc_u32 s5, s9, 0
	global_load_lds_dwordx4 v248, s[4:5]
	s_add_i32 m0, s7, 0x2000
	s_add_u32 s4, s10, 0x80
	s_addc_u32 s5, s11, 0
	global_load_lds_dwordx4 v248, s[4:5]
	s_add_i32 m0, s7, 0x2400
	s_add_u32 s4, s10, 0x8080
	s_addc_u32 s5, s11, 0
	global_load_lds_dwordx4 v248, s[4:5]
	s_add_i32 m0, s7, 0x2800
	s_add_u32 s4, s10, 0x10080
	s_addc_u32 s5, s11, 0
	global_load_lds_dwordx4 v248, s[4:5]
	s_add_i32 m0, s7, 0x2c00
	s_add_u32 s4, s10, 0x18080
	s_addc_u32 s5, s11, 0
	global_load_lds_dwordx4 v248, s[4:5]
	s_add_i32 m0, s7, 0x3000
	s_add_u32 s4, s10, 0x20080
	s_addc_u32 s5, s11, 0
	global_load_lds_dwordx4 v248, s[4:5]
	s_add_i32 m0, s7, 0x3400
	s_add_u32 s4, s10, 0x28080
	s_addc_u32 s5, s11, 0
	global_load_lds_dwordx4 v248, s[4:5]
	s_add_i32 m0, s7, 0x3800
	s_add_u32 s4, s10, 0x30080
	s_addc_u32 s5, s11, 0
	global_load_lds_dwordx4 v248, s[4:5]
	s_add_i32 m0, s7, 0x3c00
	s_add_u32 s4, s10, 0x38080
	s_addc_u32 s5, s11, 0
	global_load_lds_dwordx4 v248, s[4:5]
	v_mfma_f32_16x16x32_bf16 v[6:9], v[96:99], v[144:147], v[6:9]
	v_mfma_f32_16x16x32_bf16 v[10:13], v[96:99], v[152:155], v[10:13]
	v_mfma_f32_16x16x32_bf16 v[14:17], v[96:99], v[160:163], v[14:17]
	v_mfma_f32_16x16x32_bf16 v[18:21], v[96:99], v[168:171], v[18:21]
	v_mfma_f32_16x16x32_bf16 v[22:25], v[104:107], v[144:147], v[22:25]
	v_mfma_f32_16x16x32_bf16 v[30:33], v[104:107], v[152:155], v[30:33]
	v_mfma_f32_16x16x32_bf16 v[26:29], v[104:107], v[160:163], v[26:29]
	v_mfma_f32_16x16x32_bf16 v[34:37], v[104:107], v[168:171], v[34:37]
	v_mfma_f32_16x16x32_bf16 v[38:41], v[112:115], v[144:147], v[38:41]
	v_mfma_f32_16x16x32_bf16 v[46:49], v[112:115], v[152:155], v[46:49]
	v_mfma_f32_16x16x32_bf16 v[42:45], v[112:115], v[160:163], v[42:45]
	v_mfma_f32_16x16x32_bf16 v[54:57], v[112:115], v[168:171], v[54:57]
	v_mfma_f32_16x16x32_bf16 v[50:53], v[120:123], v[144:147], v[50:53]
	v_mfma_f32_16x16x32_bf16 v[62:65], v[120:123], v[152:155], v[62:65]
	v_mfma_f32_16x16x32_bf16 v[58:61], v[120:123], v[160:163], v[58:61]
	v_mfma_f32_16x16x32_bf16 v[66:69], v[120:123], v[168:171], v[66:69]
	v_mfma_f32_16x16x32_bf16 v[6:9], v[100:103], v[148:151], v[6:9]
	v_mfma_f32_16x16x32_bf16 v[10:13], v[100:103], v[156:159], v[10:13]
	v_mfma_f32_16x16x32_bf16 v[14:17], v[100:103], v[164:167], v[14:17]
	v_mfma_f32_16x16x32_bf16 v[18:21], v[100:103], v[172:175], v[18:21]
	v_mfma_f32_16x16x32_bf16 v[22:25], v[108:111], v[148:151], v[22:25]
	v_mfma_f32_16x16x32_bf16 v[30:33], v[108:111], v[156:159], v[30:33]
	v_mfma_f32_16x16x32_bf16 v[26:29], v[108:111], v[164:167], v[26:29]
	v_mfma_f32_16x16x32_bf16 v[34:37], v[108:111], v[172:175], v[34:37]
	v_mfma_f32_16x16x32_bf16 v[38:41], v[116:119], v[148:151], v[38:41]
	v_mfma_f32_16x16x32_bf16 v[46:49], v[116:119], v[156:159], v[46:49]
	v_mfma_f32_16x16x32_bf16 v[42:45], v[116:119], v[164:167], v[42:45]
	v_mfma_f32_16x16x32_bf16 v[54:57], v[116:119], v[172:175], v[54:57]
	v_mfma_f32_16x16x32_bf16 v[50:53], v[124:127], v[148:151], v[50:53]
	v_mfma_f32_16x16x32_bf16 v[62:65], v[124:127], v[156:159], v[62:65]
	v_mfma_f32_16x16x32_bf16 v[58:61], v[124:127], v[164:167], v[58:61]
	v_mfma_f32_16x16x32_bf16 v[66:69], v[124:127], v[172:175], v[66:69]
	s_waitcnt vmcnt(0)
	ds_read_b128 v[96:99], v249 offset:0
	ds_read_b128 v[100:103], v250 offset:0
	ds_read_b128 v[104:107], v249 offset:2048
	ds_read_b128 v[108:111], v250 offset:2048
	ds_read_b128 v[112:115], v249 offset:4096
	ds_read_b128 v[116:119], v250 offset:4096
	ds_read_b128 v[120:123], v249 offset:6144
	ds_read_b128 v[124:127], v250 offset:6144
	ds_read_b128 v[144:147], v249 offset:8192
	ds_read_b128 v[148:151], v250 offset:8192
	ds_read_b128 v[152:155], v249 offset:10240
	ds_read_b128 v[156:159], v250 offset:10240
	ds_read_b128 v[160:163], v249 offset:12288
	ds_read_b128 v[164:167], v250 offset:12288
	ds_read_b128 v[168:171], v249 offset:14336
	ds_read_b128 v[172:175], v250 offset:14336
	s_waitcnt lgkmcnt(0)
; template <bool GATE>
; __device__ __forceinline__ void sample_gemm_res(LAS unsigned char* lds, const bf16* Amat, const bf16* Bt, const bf16* Hin, bf16* Hout, float* rss_out, const bf16* PP, const float* rss_in, int bid, int tid) {
;     ...
;     for (int ks = 0; ks < 8; ++ks) { bf16x8 a[4], b[4];
; #pragma unroll
;         for (int q = 0; q < 4; ++q) { a[q] = ap[(size_t)q * 16 * 256 + ks * 4]; b[q] = bp[(size_t)q * 16 * 256 + ks * 4]; }
; #pragma unroll
;         for (int mi = 0; mi < 4; ++mi)
; #pragma unroll
;             for (int ni = 0; ni < 4; ++ni) acc[mi][ni] = __builtin_amdgcn_mfma_f32_16x16x32_bf16(a[mi], b[ni], acc[mi][ni], 0, 0, 0); }
	s_add_i32 m0, s7, 0x0
	s_add_u32 s4, s8, 0x100
	s_addc_u32 s5, s9, 0
	global_load_lds_dwordx4 v248, s[4:5]
	s_add_i32 m0, s7, 0x400
	s_add_u32 s4, s8, 0x8100
	s_addc_u32 s5, s9, 0
	global_load_lds_dwordx4 v248, s[4:5]
	s_add_i32 m0, s7, 0x800
	s_add_u32 s4, s8, 0x10100
	s_addc_u32 s5, s9, 0
	global_load_lds_dwordx4 v248, s[4:5]
	s_add_i32 m0, s7, 0xc00
	s_add_u32 s4, s8, 0x18100
	s_addc_u32 s5, s9, 0
	global_load_lds_dwordx4 v248, s[4:5]
	s_add_i32 m0, s7, 0x1000
	s_add_u32 s4, s8, 0x20100
	s_addc_u32 s5, s9, 0
	global_load_lds_dwordx4 v248, s[4:5]
	s_add_i32 m0, s7, 0x1400
	s_add_u32 s4, s8, 0x28100
	s_addc_u32 s5, s9, 0
	global_load_lds_dwordx4 v248, s[4:5]
	s_add_i32 m0, s7, 0x1800
	s_add_u32 s4, s8, 0x30100
	s_addc_u32 s5, s9, 0
	global_load_lds_dwordx4 v248, s[4:5]
	s_add_i32 m0, s7, 0x1c00
	s_add_u32 s4, s8, 0x38100
	s_addc_u32 s5, s9, 0
	global_load_lds_dwordx4 v248, s[4:5]
	s_add_i32 m0, s7, 0x2000
	s_add_u32 s4, s10, 0x100
	s_addc_u32 s5, s11, 0
	global_load_lds_dwordx4 v248, s[4:5]
	s_add_i32 m0, s7, 0x2400
	s_add_u32 s4, s10, 0x8100
	s_addc_u32 s5, s11, 0
	global_load_lds_dwordx4 v248, s[4:5]
	s_add_i32 m0, s7, 0x2800
	s_add_u32 s4, s10, 0x10100
	s_addc_u32 s5, s11, 0
	global_load_lds_dwordx4 v248, s[4:5]
	s_add_i32 m0, s7, 0x2c00
	s_add_u32 s4, s10, 0x18100
	s_addc_u32 s5, s11, 0
	global_load_lds_dwordx4 v248, s[4:5]
	s_add_i32 m0, s7, 0x3000
	s_add_u32 s4, s10, 0x20100
	s_addc_u32 s5, s11, 0
	global_load_lds_dwordx4 v248, s[4:5]
	s_add_i32 m0, s7, 0x3400
	s_add_u32 s4, s10, 0x28100
	s_addc_u32 s5, s11, 0
	global_load_lds_dwordx4 v248, s[4:5]
	s_add_i32 m0, s7, 0x3800
	s_add_u32 s4, s10, 0x30100
	s_addc_u32 s5, s11, 0
	global_load_lds_dwordx4 v248, s[4:5]
	s_add_i32 m0, s7, 0x3c00
	s_add_u32 s4, s10, 0x38100
	s_addc_u32 s5, s11, 0
	global_load_lds_dwordx4 v248, s[4:5]
	v_mfma_f32_16x16x32_bf16 v[6:9], v[96:99], v[144:147], v[6:9]
	v_mfma_f32_16x16x32_bf16 v[10:13], v[96:99], v[152:155], v[10:13]
	v_mfma_f32_16x16x32_bf16 v[14:17], v[96:99], v[160:163], v[14:17]
	v_mfma_f32_16x16x32_bf16 v[18:21], v[96:99], v[168:171], v[18:21]
	v_mfma_f32_16x16x32_bf16 v[22:25], v[104:107], v[144:147], v[22:25]
	v_mfma_f32_16x16x32_bf16 v[30:33], v[104:107], v[152:155], v[30:33]
	v_mfma_f32_16x16x32_bf16 v[26:29], v[104:107], v[160:163], v[26:29]
	v_mfma_f32_16x16x32_bf16 v[34:37], v[104:107], v[168:171], v[34:37]
	v_mfma_f32_16x16x32_bf16 v[38:41], v[112:115], v[144:147], v[38:41]
	v_mfma_f32_16x16x32_bf16 v[46:49], v[112:115], v[152:155], v[46:49]
	v_mfma_f32_16x16x32_bf16 v[42:45], v[112:115], v[160:163], v[42:45]
	v_mfma_f32_16x16x32_bf16 v[54:57], v[112:115], v[168:171], v[54:57]
	v_mfma_f32_16x16x32_bf16 v[50:53], v[120:123], v[144:147], v[50:53]
	v_mfma_f32_16x16x32_bf16 v[62:65], v[120:123], v[152:155], v[62:65]
	v_mfma_f32_16x16x32_bf16 v[58:61], v[120:123], v[160:163], v[58:61]
	v_mfma_f32_16x16x32_bf16 v[66:69], v[120:123], v[168:171], v[66:69]
	v_mfma_f32_16x16x32_bf16 v[6:9], v[100:103], v[148:151], v[6:9]
	v_mfma_f32_16x16x32_bf16 v[10:13], v[100:103], v[156:159], v[10:13]
	v_mfma_f32_16x16x32_bf16 v[14:17], v[100:103], v[164:167], v[14:17]
	v_mfma_f32_16x16x32_bf16 v[18:21], v[100:103], v[172:175], v[18:21]
	v_mfma_f32_16x16x32_bf16 v[22:25], v[108:111], v[148:151], v[22:25]
	v_mfma_f32_16x16x32_bf16 v[30:33], v[108:111], v[156:159], v[30:33]
	v_mfma_f32_16x16x32_bf16 v[26:29], v[108:111], v[164:167], v[26:29]
	v_mfma_f32_16x16x32_bf16 v[34:37], v[108:111], v[172:175], v[34:37]
	v_mfma_f32_16x16x32_bf16 v[38:41], v[116:119], v[148:151], v[38:41]
	v_mfma_f32_16x16x32_bf16 v[46:49], v[116:119], v[156:159], v[46:49]
	v_mfma_f32_16x16x32_bf16 v[42:45], v[116:119], v[164:167], v[42:45]
	v_mfma_f32_16x16x32_bf16 v[54:57], v[116:119], v[172:175], v[54:57]
	v_mfma_f32_16x16x32_bf16 v[50:53], v[124:127], v[148:151], v[50:53]
	v_mfma_f32_16x16x32_bf16 v[62:65], v[124:127], v[156:159], v[62:65]
	v_mfma_f32_16x16x32_bf16 v[58:61], v[124:127], v[164:167], v[58:61]
	v_mfma_f32_16x16x32_bf16 v[66:69], v[124:127], v[172:175], v[66:69]
	s_waitcnt vmcnt(0)
	ds_read_b128 v[96:99], v249 offset:0
	ds_read_b128 v[100:103], v250 offset:0
	ds_read_b128 v[104:107], v249 offset:2048
	ds_read_b128 v[108:111], v250 offset:2048
	ds_read_b128 v[112:115], v249 offset:4096
	ds_read_b128 v[116:119], v250 offset:4096
	ds_read_b128 v[120:123], v249 offset:6144
	ds_read_b128 v[124:127], v250 offset:6144
	ds_read_b128 v[144:147], v249 offset:8192
	ds_read_b128 v[148:151], v250 offset:8192
	ds_read_b128 v[152:155], v249 offset:10240
	ds_read_b128 v[156:159], v250 offset:10240
	ds_read_b128 v[160:163], v249 offset:12288
	ds_read_b128 v[164:167], v250 offset:12288
	ds_read_b128 v[168:171], v249 offset:14336
	ds_read_b128 v[172:175], v250 offset:14336
	s_waitcnt lgkmcnt(0)
; #define LAS __attribute__((address_space(3)))
; template <bool GATE>
; __device__ __forceinline__ void sample_gemm_res(LAS unsigned char* lds, const bf16* Amat, const bf16* Bt, const bf16* Hin, bf16* Hout, float* rss_out, const bf16* PP, const float* rss_in, int bid, int tid) {
;     ...
;     for (int ks = 0; ks < 8; ++ks) { bf16x8 a[4], b[4];
; #pragma unroll
;         for (int q = 0; q < 4; ++q) { a[q] = ap[(size_t)q * 16 * 256 + ks * 4]; b[q] = bp[(size_t)q * 16 * 256 + ks * 4]; }
; #pragma unroll
;         for (int mi = 0; mi < 4; ++mi)
; #pragma unroll
;             for (int ni = 0; ni < 4; ++ni) acc[mi][ni] = __builtin_amdgcn_mfma_f32_16x16x32_bf16(a[mi], b[ni], acc[mi][ni], 0, 0, 0); }
;     LAS float* red = (LAS float*)lds;
;     __syncthreads();
	s_add_i32 m0, s7, 0x0
	s_add_u32 s4, s8, 0x180
	s_addc_u32 s5, s9, 0
	global_load_lds_dwordx4 v248, s[4:5]
	s_add_i32 m0, s7, 0x400
	s_add_u32 s4, s8, 0x8180
	s_addc_u32 s5, s9, 0
	global_load_lds_dwordx4 v248, s[4:5]
	s_add_i32 m0, s7, 0x800
	s_add_u32 s4, s8, 0x10180
	s_addc_u32 s5, s9, 0
	global_load_lds_dwordx4 v248, s[4:5]
	s_add_i32 m0, s7, 0xc00
	s_add_u32 s4, s8, 0x18180
	s_addc_u32 s5, s9, 0
	global_load_lds_dwordx4 v248, s[4:5]
	s_add_i32 m0, s7, 0x1000
	s_add_u32 s4, s8, 0x20180
	s_addc_u32 s5, s9, 0
	global_load_lds_dwordx4 v248, s[4:5]
	s_add_i32 m0, s7, 0x1400
	s_add_u32 s4, s8, 0x28180
	s_addc_u32 s5, s9, 0
	global_load_lds_dwordx4 v248, s[4:5]
	s_add_i32 m0, s7, 0x1800
	s_add_u32 s4, s8, 0x30180
	s_addc_u32 s5, s9, 0
	global_load_lds_dwordx4 v248, s[4:5]
	s_add_i32 m0, s7, 0x1c00
	s_add_u32 s4, s8, 0x38180
	s_addc_u32 s5, s9, 0
	global_load_lds_dwordx4 v248, s[4:5]
	s_add_i32 m0, s7, 0x2000
	s_add_u32 s4, s10, 0x180
	s_addc_u32 s5, s11, 0
	global_load_lds_dwordx4 v248, s[4:5]
	s_add_i32 m0, s7, 0x2400
	s_add_u32 s4, s10, 0x8180
	s_addc_u32 s5, s11, 0
	global_load_lds_dwordx4 v248, s[4:5]
	s_add_i32 m0, s7, 0x2800
	s_add_u32 s4, s10, 0x10180
	s_addc_u32 s5, s11, 0
	global_load_lds_dwordx4 v248, s[4:5]
	s_add_i32 m0, s7, 0x2c00
	s_add_u32 s4, s10, 0x18180
	s_addc_u32 s5, s11, 0
	global_load_lds_dwordx4 v248, s[4:5]
	s_add_i32 m0, s7, 0x3000
	s_add_u32 s4, s10, 0x20180
	s_addc_u32 s5, s11, 0
	global_load_lds_dwordx4 v248, s[4:5]
	s_add_i32 m0, s7, 0x3400
	s_add_u32 s4, s10, 0x28180
	s_addc_u32 s5, s11, 0
	global_load_lds_dwordx4 v248, s[4:5]
	s_add_i32 m0, s7, 0x3800
	s_add_u32 s4, s10, 0x30180
	s_addc_u32 s5, s11, 0
	global_load_lds_dwordx4 v248, s[4:5]
	s_add_i32 m0, s7, 0x3c00
	s_add_u32 s4, s10, 0x38180
	s_addc_u32 s5, s11, 0
	global_load_lds_dwordx4 v248, s[4:5]
	v_mfma_f32_16x16x32_bf16 v[6:9], v[96:99], v[144:147], v[6:9]
	v_mfma_f32_16x16x32_bf16 v[10:13], v[96:99], v[152:155], v[10:13]
	v_mfma_f32_16x16x32_bf16 v[14:17], v[96:99], v[160:163], v[14:17]
	v_mfma_f32_16x16x32_bf16 v[18:21], v[96:99], v[168:171], v[18:21]
	v_mfma_f32_16x16x32_bf16 v[22:25], v[104:107], v[144:147], v[22:25]
	v_mfma_f32_16x16x32_bf16 v[30:33], v[104:107], v[152:155], v[30:33]
	v_mfma_f32_16x16x32_bf16 v[26:29], v[104:107], v[160:163], v[26:29]
	v_mfma_f32_16x16x32_bf16 v[34:37], v[104:107], v[168:171], v[34:37]
	v_mfma_f32_16x16x32_bf16 v[38:41], v[112:115], v[144:147], v[38:41]
	v_mfma_f32_16x16x32_bf16 v[46:49], v[112:115], v[152:155], v[46:49]
	v_mfma_f32_16x16x32_bf16 v[42:45], v[112:115], v[160:163], v[42:45]
	v_mfma_f32_16x16x32_bf16 v[54:57], v[112:115], v[168:171], v[54:57]
	v_mfma_f32_16x16x32_bf16 v[50:53], v[120:123], v[144:147], v[50:53]
	v_mfma_f32_16x16x32_bf16 v[62:65], v[120:123], v[152:155], v[62:65]
	v_mfma_f32_16x16x32_bf16 v[58:61], v[120:123], v[160:163], v[58:61]
	v_mfma_f32_16x16x32_bf16 v[66:69], v[120:123], v[168:171], v[66:69]
	v_mfma_f32_16x16x32_bf16 v[6:9], v[100:103], v[148:151], v[6:9]
	v_mfma_f32_16x16x32_bf16 v[10:13], v[100:103], v[156:159], v[10:13]
	v_mfma_f32_16x16x32_bf16 v[14:17], v[100:103], v[164:167], v[14:17]
	v_mfma_f32_16x16x32_bf16 v[18:21], v[100:103], v[172:175], v[18:21]
	v_mfma_f32_16x16x32_bf16 v[22:25], v[108:111], v[148:151], v[22:25]
	v_mfma_f32_16x16x32_bf16 v[30:33], v[108:111], v[156:159], v[30:33]
	v_mfma_f32_16x16x32_bf16 v[26:29], v[108:111], v[164:167], v[26:29]
	v_mfma_f32_16x16x32_bf16 v[34:37], v[108:111], v[172:175], v[34:37]
	v_mfma_f32_16x16x32_bf16 v[38:41], v[116:119], v[148:151], v[38:41]
	v_mfma_f32_16x16x32_bf16 v[46:49], v[116:119], v[156:159], v[46:49]
	v_mfma_f32_16x16x32_bf16 v[42:45], v[116:119], v[164:167], v[42:45]
	v_mfma_f32_16x16x32_bf16 v[54:57], v[116:119], v[172:175], v[54:57]
	v_mfma_f32_16x16x32_bf16 v[50:53], v[124:127], v[148:151], v[50:53]
	v_mfma_f32_16x16x32_bf16 v[62:65], v[124:127], v[156:159], v[62:65]
	v_mfma_f32_16x16x32_bf16 v[58:61], v[124:127], v[164:167], v[58:61]
	v_mfma_f32_16x16x32_bf16 v[66:69], v[124:127], v[172:175], v[66:69]
	s_waitcnt vmcnt(0)
	ds_read_b128 v[96:99], v249 offset:0
	ds_read_b128 v[100:103], v250 offset:0
	ds_read_b128 v[104:107], v249 offset:2048
	ds_read_b128 v[108:111], v250 offset:2048
	ds_read_b128 v[112:115], v249 offset:4096
	ds_read_b128 v[116:119], v250 offset:4096
	ds_read_b128 v[120:123], v249 offset:6144
	ds_read_b128 v[124:127], v250 offset:6144
	ds_read_b128 v[144:147], v249 offset:8192
	ds_read_b128 v[148:151], v250 offset:8192
	ds_read_b128 v[152:155], v249 offset:10240
	ds_read_b128 v[156:159], v250 offset:10240
	ds_read_b128 v[160:163], v249 offset:12288
	ds_read_b128 v[164:167], v250 offset:12288
	ds_read_b128 v[168:171], v249 offset:14336
	ds_read_b128 v[172:175], v250 offset:14336
	s_waitcnt lgkmcnt(0)
	v_mfma_f32_16x16x32_bf16 v[6:9], v[96:99], v[144:147], v[6:9]
	v_mfma_f32_16x16x32_bf16 v[10:13], v[96:99], v[152:155], v[10:13]
	v_mfma_f32_16x16x32_bf16 v[14:17], v[96:99], v[160:163], v[14:17]
	v_mfma_f32_16x16x32_bf16 v[18:21], v[96:99], v[168:171], v[18:21]
	v_mfma_f32_16x16x32_bf16 v[22:25], v[104:107], v[144:147], v[22:25]
	v_mfma_f32_16x16x32_bf16 v[30:33], v[104:107], v[152:155], v[30:33]
	v_mfma_f32_16x16x32_bf16 v[26:29], v[104:107], v[160:163], v[26:29]
	v_mfma_f32_16x16x32_bf16 v[34:37], v[104:107], v[168:171], v[34:37]
	v_mfma_f32_16x16x32_bf16 v[38:41], v[112:115], v[144:147], v[38:41]
	v_mfma_f32_16x16x32_bf16 v[46:49], v[112:115], v[152:155], v[46:49]
	v_mfma_f32_16x16x32_bf16 v[42:45], v[112:115], v[160:163], v[42:45]
	v_mfma_f32_16x16x32_bf16 v[54:57], v[112:115], v[168:171], v[54:57]
	v_mfma_f32_16x16x32_bf16 v[50:53], v[120:123], v[144:147], v[50:53]
	v_mfma_f32_16x16x32_bf16 v[62:65], v[120:123], v[152:155], v[62:65]
	v_mfma_f32_16x16x32_bf16 v[58:61], v[120:123], v[160:163], v[58:61]
	v_mfma_f32_16x16x32_bf16 v[66:69], v[120:123], v[168:171], v[66:69]
	v_mfma_f32_16x16x32_bf16 v[6:9], v[100:103], v[148:151], v[6:9]
	v_mfma_f32_16x16x32_bf16 v[10:13], v[100:103], v[156:159], v[10:13]
	v_mfma_f32_16x16x32_bf16 v[14:17], v[100:103], v[164:167], v[14:17]
	v_mfma_f32_16x16x32_bf16 v[18:21], v[100:103], v[172:175], v[18:21]
	v_mfma_f32_16x16x32_bf16 v[22:25], v[108:111], v[148:151], v[22:25]
	v_mfma_f32_16x16x32_bf16 v[30:33], v[108:111], v[156:159], v[30:33]
	v_mfma_f32_16x16x32_bf16 v[26:29], v[108:111], v[164:167], v[26:29]
	v_mfma_f32_16x16x32_bf16 v[34:37], v[108:111], v[172:175], v[34:37]
	v_mfma_f32_16x16x32_bf16 v[38:41], v[116:119], v[148:151], v[38:41]
	v_mfma_f32_16x16x32_bf16 v[46:49], v[116:119], v[156:159], v[46:49]
	v_mfma_f32_16x16x32_bf16 v[42:45], v[116:119], v[164:167], v[42:45]
	v_mfma_f32_16x16x32_bf16 v[54:57], v[116:119], v[172:175], v[54:57]
	v_mfma_f32_16x16x32_bf16 v[50:53], v[124:127], v[148:151], v[50:53]
	v_mfma_f32_16x16x32_bf16 v[62:65], v[124:127], v[156:159], v[62:65]
	v_mfma_f32_16x16x32_bf16 v[58:61], v[124:127], v[164:167], v[58:61]
	v_mfma_f32_16x16x32_bf16 v[66:69], v[124:127], v[172:175], v[66:69]
	v_add_u32_e32 v0, 0x1000, v89
	s_barrier
; __device__ __forceinline__ unsigned cvtpk(float lo, float hi) { f32x2_t v = {lo, hi}; bf16x2_t b = __builtin_convertvector(v, bf16x2_t); return __builtin_bit_cast(unsigned, b); }
; template <bool GATE>
; __device__ __forceinline__ void sample_gemm_res(LAS unsigned char* lds, const bf16* Amat, const bf16* Bt, const bf16* Hin, bf16* Hout, float* rss_out, const bf16* PP, const float* rss_in, int bid, int tid) {
;     ...
; #pragma unroll
;     for (int mi = 0; mi < 4; ++mi)
; #pragma unroll
;         for (int ni = 0; ni < 4; ++ni)
; #pragma unroll
;             for (int i = 0; i < 4; ++i) red[(wave * 64 + 16 * mi + kg * 4 + i) * 65 + 16 * ni + lr] = acc[mi][ni][i];
;     __syncthreads();
;     { const int row = tid >> 3, c8 = (tid & 7) * 8, grow = m0 + row; float v[8];
; #pragma unroll
;       for (int e = 0; e < 8; ++e) { float sacc = 0.f;
; #pragma unroll
;           for (int w = 0; w < 8; ++w) sacc += red[(w * 64 + row) * 65 + c8 + e];
;           v[e] = sacc; }
;       float sc = 1.f; if (GATE) sc = rsqrtf(rsi * (1.f / 2048.f) + 1e-6f);
;       const size_t p = (size_t)grow * 2048 + n0 + c8;
;       const unsigned hws[4] = {hw.x, hw.y, hw.z, hw.w}, pws[4] = {pw.x, pw.y, pw.z, pw.w}; unsigned ow[4]; float sq = 0.f;
; #pragma unroll
;       for (int e2 = 0; e2 < 4; ++e2) { float h0 = __uint_as_float(hws[e2] << 16), h1 = __uint_as_float(hws[e2] & 0xffff0000u);
;           if (GATE) { h0 += __builtin_amdgcn_rcpf(1.f + __expf(-sc * v[2 * e2])) * __uint_as_float(pws[e2] << 16); h1 += __builtin_amdgcn_rcpf(1.f + __expf(-sc * v[2 * e2 + 1])) * __uint_as_float(pws[e2] & 0xffff0000u); }
;           else { h0 += v[2 * e2]; h1 += v[2 * e2 + 1]; }
;           sq += h0 * h0 + h1 * h1; ow[e2] = cvtpk(h0, h1); }
;       *(u32x4*)(Hout + p) = (u32x4){ow[0], ow[1], ow[2], ow[3]};
;       sq += __shfl_xor(sq, 1); sq += __shfl_xor(sq, 2); sq += __shfl_xor(sq, 4);
;       if ((tid & 7) == 0) atomicAdd(rss_out + grow, sq); }
;     __syncthreads();
	ds_write2_b32 v89, v6, v10 offset1:16
	ds_write2_b32 v89, v7, v11 offset0:65 offset1:81
	ds_write2_b32 v89, v8, v12 offset0:130 offset1:146
	ds_write2_b32 v89, v9, v13 offset0:195 offset1:211
	ds_write2_b32 v89, v14, v18 offset0:32 offset1:48
	ds_write2_b32 v89, v15, v19 offset0:97 offset1:113
	ds_write2_b32 v89, v16, v20 offset0:162 offset1:178
	ds_write2_b32 v89, v17, v21 offset0:227 offset1:243
	ds_write2_b32 v0, v22, v30 offset0:16 offset1:32
	ds_write2_b32 v0, v23, v31 offset0:81 offset1:97
	ds_write2_b32 v0, v24, v32 offset0:146 offset1:162
	ds_write2_b32 v0, v25, v33 offset0:211 offset1:227
	ds_write2_b32 v0, v26, v34 offset0:48 offset1:64
	ds_write2_b32 v0, v27, v35 offset0:113 offset1:129
	ds_write2_b32 v0, v28, v36 offset0:178 offset1:194
	v_add_u32_e32 v0, 0x1200, v89
	ds_write2_b32 v0, v29, v37 offset0:115 offset1:131
	v_add_u32_e32 v0, 0x2000, v89
	ds_write2_b32 v0, v38, v46 offset0:32 offset1:48
	ds_write2_b32 v0, v39, v47 offset0:97 offset1:113
	ds_write2_b32 v0, v40, v48 offset0:162 offset1:178
	ds_write2_b32 v0, v41, v49 offset0:227 offset1:243
	ds_write2_b32 v0, v42, v54 offset0:64 offset1:80
	ds_write2_b32 v0, v43, v55 offset0:129 offset1:145
	ds_write2_b32 v0, v44, v56 offset0:194 offset1:210
	v_add_u32_e32 v0, 0x2400, v89
	ds_write2_b32 v0, v45, v57 offset0:3 offset1:19
	v_add_u32_e32 v0, 0x3000, v89
	v_add_u32_e32 v6, 0x3200, v89
	ds_write2_b32 v0, v50, v62 offset0:48 offset1:64
	ds_write2_b32 v0, v51, v63 offset0:113 offset1:129
	ds_write2_b32 v0, v52, v64 offset0:178 offset1:194
	ds_write2_b32 v6, v53, v65 offset0:115 offset1:131
	ds_write2_b32 v0, v58, v66 offset0:80 offset1:96
	ds_write2_b32 v0, v59, v67 offset0:145 offset1:161
	ds_write2_b32 v0, v60, v68 offset0:210 offset1:226
	v_add_u32_e32 v0, 0x3400, v89
	ds_write2_b32 v0, v61, v69 offset0:19 offset1:35
	v_add_u32_e32 v0, v85, v90
	s_waitcnt lgkmcnt(0)
	s_barrier
	ds_read2_b32 v[6:7], v0 offset1:1
	v_add_u32_e32 v8, 0x4100, v0
	v_add_u32_e32 v10, 0x8200, v0
	v_add_u32_e32 v12, 0xc300, v0
	ds_read2_b32 v[8:9], v8 offset1:1
	ds_read2_b32 v[10:11], v10 offset1:1
	ds_read2_b32 v[12:13], v12 offset1:1
	ds_read2_b32 v[14:15], v0 offset0:2 offset1:3
	ds_read2_b32 v[16:17], v0 offset0:4 offset1:5
	ds_read2_b32 v[18:19], v0 offset0:6 offset1:7
	s_waitcnt lgkmcnt(6)
	v_pk_add_f32 v[6:7], v[6:7], 0 op_sel_hi:[1,0]
	ds_read2_b32 v[20:21], v92 offset1:1
	s_waitcnt lgkmcnt(6)
	v_pk_add_f32 v[6:7], v[6:7], v[8:9]
	ds_read2_b32 v[8:9], v93 offset1:1
	s_waitcnt lgkmcnt(6)
	v_pk_add_f32 v[6:7], v[6:7], v[10:11]
	s_waitcnt lgkmcnt(4)
	v_pk_add_f32 v[14:15], v[14:15], 0 op_sel_hi:[1,0]
	v_pk_add_f32 v[6:7], v[6:7], v[12:13]
	v_add_u32_e32 v42, 0xc308, v0
	s_waitcnt lgkmcnt(1)
	v_pk_add_f32 v[6:7], v[6:7], v[20:21]
	ds_read2_b32 v[10:11], v92 offset0:2 offset1:3
	ds_read2_b32 v[12:13], v92 offset0:4 offset1:5
	ds_read2_b32 v[20:21], v92 offset0:6 offset1:7
	s_waitcnt lgkmcnt(3)
	v_pk_add_f32 v[6:7], v[6:7], v[8:9]
	ds_read2_b32 v[8:9], v94 offset1:1
	ds_read2_b32 v[22:23], v95 offset1:1
	ds_read2_b32 v[24:25], v93 offset0:2 offset1:3
	ds_read2_b32 v[26:27], v93 offset0:4 offset1:5
	ds_read2_b32 v[28:29], v93 offset0:6 offset1:7
	s_waitcnt lgkmcnt(4)
	v_pk_add_f32 v[6:7], v[6:7], v[8:9]
	ds_read2_b32 v[8:9], v94 offset0:2 offset1:3
	ds_read2_b32 v[30:31], v94 offset0:4 offset1:5
	ds_read2_b32 v[32:33], v94 offset0:6 offset1:7
	s_waitcnt lgkmcnt(6)
	v_pk_add_f32 v[6:7], v[6:7], v[22:23]
	v_lshlrev_b32_e32 v22, 16, v2
	v_and_b32_e32 v23, 0xffff0000, v2
	v_add_u32_e32 v2, 0x4108, v0
	ds_read2_b32 v[34:35], v2 offset1:1
	v_add_u32_e32 v2, 0x8208, v0
	ds_read2_b32 v[36:37], v95 offset0:2 offset1:3
	ds_read2_b32 v[38:39], v95 offset0:4 offset1:5
	ds_read2_b32 v[40:41], v95 offset0:6 offset1:7
	v_add_u32_e32 v46, 0x8210, v0
	v_pk_add_f32 v[6:7], v[6:7], v[22:23]
	s_waitcnt lgkmcnt(3)
	v_pk_add_f32 v[14:15], v[14:15], v[34:35]
	ds_read2_b32 v[34:35], v2 offset1:1
	ds_read2_b32 v[42:43], v42 offset1:1
	v_add_u32_e32 v2, 0x4110, v0
	ds_read2_b32 v[44:45], v2 offset1:1
	ds_read2_b32 v[46:47], v46 offset1:1
	v_lshlrev_b32_e32 v2, 16, v3
	s_waitcnt lgkmcnt(3)
	v_pk_add_f32 v[14:15], v[14:15], v[34:35]
	v_and_b32_e32 v3, 0xffff0000, v3
	s_waitcnt lgkmcnt(2)
	v_pk_add_f32 v[14:15], v[14:15], v[42:43]
	v_pk_mul_f32 v[22:23], v[6:7], v[6:7]
	v_pk_add_f32 v[10:11], v[14:15], v[10:11]
	v_add_u32_e32 v14, 0xc310, v0
	ds_read2_b32 v[14:15], v14 offset1:1
	v_pk_add_f32 v[10:11], v[10:11], v[24:25]
	v_add_u32_e32 v24, 0x8218, v0
	v_pk_add_f32 v[8:9], v[10:11], v[8:9]
	v_pk_add_f32 v[10:11], v[16:17], 0 op_sel_hi:[1,0]
	v_add_u32_e32 v16, 0x4118, v0
	s_waitcnt lgkmcnt(2)
	v_pk_add_f32 v[10:11], v[10:11], v[44:45]
	v_add_u32_e32 v0, 0xc318, v0
	ds_read2_b32 v[16:17], v16 offset1:1
	ds_read2_b32 v[24:25], v24 offset1:1
	ds_read2_b32 v[34:35], v0 offset1:1
	s_waitcnt lgkmcnt(4)
	v_pk_add_f32 v[10:11], v[10:11], v[46:47]
	v_pk_add_f32 v[8:9], v[8:9], v[36:37]
	s_waitcnt lgkmcnt(3)
	v_pk_add_f32 v[10:11], v[10:11], v[14:15]
	v_pk_add_f32 v[14:15], v[18:19], 0 op_sel_hi:[1,0]
	v_pk_add_f32 v[10:11], v[10:11], v[12:13]
	s_waitcnt lgkmcnt(2)
	v_pk_add_f32 v[14:15], v[14:15], v[16:17]
	v_pk_add_f32 v[10:11], v[10:11], v[26:27]
	s_waitcnt lgkmcnt(1)
	v_pk_add_f32 v[14:15], v[14:15], v[24:25]
	v_pk_add_f32 v[10:11], v[10:11], v[30:31]
	s_waitcnt lgkmcnt(0)
	v_pk_add_f32 v[14:15], v[14:15], v[34:35]
	v_pk_add_f32 v[2:3], v[8:9], v[2:3]
	v_pk_add_f32 v[14:15], v[14:15], v[20:21]
	v_pk_add_f32 v[10:11], v[10:11], v[38:39]
	v_pk_add_f32 v[14:15], v[14:15], v[28:29]
	v_lshlrev_b32_e32 v12, 16, v4
	v_and_b32_e32 v13, 0xffff0000, v4
	v_pk_add_f32 v[14:15], v[14:15], v[32:33]
	v_pk_mul_f32 v[8:9], v[2:3], v[2:3]
	v_pk_add_f32 v[10:11], v[10:11], v[12:13]
	v_pk_add_f32 v[14:15], v[14:15], v[40:41]
	v_lshlrev_b32_e32 v4, 16, v5
	v_and_b32_e32 v5, 0xffff0000, v5
	v_pk_mul_f32 v[12:13], v[10:11], v[10:11]
	v_pk_add_f32 v[14:15], v[14:15], v[4:5]
	v_add_f32_e32 v0, v8, v9
	v_add_f32_e32 v8, v22, v23
	v_pk_mul_f32 v[4:5], v[14:15], v[14:15]
	v_add_f32_e32 v0, v8, v0
	v_add_f32_e32 v8, v12, v13
	v_add_f32_e32 v0, v0, v8
	v_add_f32_e32 v4, v4, v5
	v_add_f32_e32 v0, v0, v4
	ds_bpermute_b32 v4, v86, v0
	v_cvt_pk_bf16_f32 v5, v2, v3
	s_waitcnt lgkmcnt(0)
	v_add_f32_e32 v0, v0, v4
	ds_bpermute_b32 v8, v87, v0
	v_cvt_pk_bf16_f32 v4, v6, v7
	v_cvt_pk_bf16_f32 v6, v10, v11
	v_cvt_pk_bf16_f32 v7, v14, v15
	s_waitcnt lgkmcnt(0)
	v_add_f32_e32 v0, v0, v8
	ds_bpermute_b32 v2, v88, v0
	v_lshl_add_u64 v[8:9], v[78:79], 1, s[48:49]
	global_store_dwordx4 v[8:9], v[4:7], off
	s_and_saveexec_b64 s[0:1], vcc
	s_cbranch_execz .LBB0_114
	s_waitcnt lgkmcnt(0)
	v_add_f32_e32 v0, v0, v2
	v_lshl_add_u64 v[2:3], v[76:77], 2, s[50:51]
	global_atomic_add_f32 v[2:3], v0, off
	s_branch .LBB0_114

; __device__ __forceinline__ unsigned f2bf(float f) { return cvtpk(f, 0.f) & 0xffffu; }
; __device__ __forceinline__ int crow(int reg, int h) { return (reg & 3) + 8 * (reg >> 2) + 4 * h; }
; __device__ __forceinline__ void phase_ab_rec(const KP kp, const int bid, const int G, int j, int li, LAS unsigned char* lds, int tid0) {
;     ...
;                     bf16* yo = OGLA + (size_t)(b * 2048 + n * 64) * 1024 + h * 256 + 32 * nt + r;
; #pragma unroll
;                     for (int i = 0; i < 16; ++i) { yo[(size_t)crow(i, hp) * 1024] = (bf16)f2bf(O0[i]); yo[(size_t)(32 + crow(i, hp)) * 1024] = (bf16)f2bf(O1[i]); }
;                 }
;                 asm volatile("s_waitcnt vmcnt(0)" ::: "memory"); __syncthreads();
;             }
.Lgla_scan_join:
	s_add_u32 s8, s8, 0x20000
	s_addc_u32 s9, s9, 0
	s_add_i32 s18, s18, 1
	s_add_i32 s19, s19, 4
	s_cmp_eq_u32 s8, 0x400000
	s_waitcnt lgkmcnt(0)
	s_barrier
	s_cbranch_scc1 .LBB0_236

; #define LAS __attribute__((address_space(3)))
; #define MFMA32(a, b, c) __builtin_amdgcn_mfma_f32_32x32x16_bf16((a), (b), (c), 0, 0, 0)
; #define PACK_ACC(x, S_) __builtin_bit_cast(bf16x8, (u32x4){cvtpk((x)[8 * (S_)], (x)[8 * (S_) + 1]), cvtpk((x)[8 * (S_) + 2], (x)[8 * (S_) + 3]), cvtpk((x)[8 * (S_) + 4], (x)[8 * (S_) + 5]), cvtpk((x)[8 * (S_) + 6], (x)[8 * (S_) + 7])})
; __device__ __forceinline__ void phase_ab_rec(const KP kp, const int bid, const int G, int j, int li, LAS unsigned char* lds, int tid0) {
;     ...
;                 if (wave < 4) {
;                     const LAS bf16x8* F = (const LAS bf16x8*)(lds + (n & 1) * GBUF) + lane;
;                     const LAS float* ge = (const LAS float*)(lds + (n & 1) * GBUF + 56 * 1024) + 4 * hp;
;                     const bf16x8 sb0 = PACK_ACC(S0, 0), sb1 = PACK_ACC(S0, 1), sb2 = PACK_ACC(S1, 0), sb3 = PACK_ACC(S1, 1), sb4 = PACK_ACC(S2, 0), sb5 = PACK_ACC(S2, 1), sb6 = PACK_ACC(S3, 0), sb7 = PACK_ACC(S3, 1);
;                     f32x16 O0, O1;
; #pragma unroll
;                     for (int i = 0; i < 16; ++i) { O0[i] = 0.f; O1[i] = 0.f; }
;                     O0 = MFMA32(F[0 * 64], sb0, O0); O0 = MFMA32(F[1 * 64], sb1, O0); O0 = MFMA32(F[2 * 64], sb2, O0); O0 = MFMA32(F[3 * 64], sb3, O0);
;                     O0 = MFMA32(F[4 * 64], sb4, O0); O0 = MFMA32(F[5 * 64], sb5, O0); O0 = MFMA32(F[6 * 64], sb6, O0); O0 = MFMA32(F[7 * 64], sb7, O0);
;                     O1 = MFMA32(F[8 * 64], sb0, O1); O1 = MFMA32(F[9 * 64], sb1, O1); O1 = MFMA32(F[10 * 64], sb2, O1); O1 = MFMA32(F[11 * 64], sb3, O1);
;                     O1 = MFMA32(F[12 * 64], sb4, O1); O1 = MFMA32(F[13 * 64], sb5, O1); O1 = MFMA32(F[14 * 64], sb6, O1); O1 = MFMA32(F[15 * 64], sb7, O1);
;                     bf16x8 vb[4];
; #pragma unroll
;                     for (int ks = 0; ks < 4; ++ks) vb[ks] = F[(40 + wave * 4 + ks) * 64];
;                     O0 = MFMA32(F[32 * 64], vb[0], O0); O0 = MFMA32(F[33 * 64], vb[1], O0);
; #pragma unroll
;                     for (int ks = 0; ks < 4; ++ks) O1 = MFMA32(F[(36 + ks) * 64], vb[ks], O1);
; #pragma unroll
;                     for (int q = 0; q < 4; ++q) { const f32x4 g0 = *(const LAS f32x4*)(ge + 8 * q), g1 = *(const LAS f32x4*)(ge + 32 + 8 * q), g2 = *(const LAS f32x4*)(ge + 64 + 8 * q), g3 = *(const LAS f32x4*)(ge + 96 + 8 * q);
.LBB0_234:
	s_bitcmp1_b32 s18, 0
	s_cselect_b32 s20, 0, 0xe400
	s_add_i32 s20, s20, 0
	v_lshl_add_u32 v0, v198, 4, s20
	v_cvt_pk_bf16_f32 v82, v34, v35
	v_cvt_pk_bf16_f32 v83, v36, v37
	v_cvt_pk_bf16_f32 v84, v38, v39
	v_cvt_pk_bf16_f32 v85, v40, v41
	ds_read_b128 v[66:69], v0
	ds_read_b128 v[86:89], v0 offset:1024
	ds_read_b128 v[90:93], v0 offset:2048
	ds_read_b128 v[94:97], v0 offset:3072
	ds_read_b128 v[174:177], v0 offset:4096
	ds_read_b128 v[178:181], v0 offset:5120
	ds_read_b128 v[202:205], v0 offset:6144
	ds_read_b128 v[142:145], v0 offset:7168
	ds_read_b128 v[206:209], v0 offset:8192
	ds_read_b128 v[170:173], v0 offset:9216
	ds_read_b128 v[146:149], v0 offset:10240
	ds_read_b128 v[150:153], v0 offset:11264
	ds_read_b128 v[154:157], v0 offset:12288
	ds_read_b128 v[158:161], v0 offset:13312
	ds_read_b128 v[162:165], v0 offset:14336
	ds_read_b128 v[166:169], v0 offset:15360
	v_add_u32_e32 v70, s0, v0
	ds_read_b128 v[110:113], v70 offset:40960
	ds_read_b128 v[106:109], v70 offset:41984
	ds_read_b128 v[102:105], v70 offset:43008
	ds_read_b128 v[98:101], v70 offset:44032
	s_waitcnt lgkmcnt(0)
	v_mfma_f32_32x32x16_bf16 v[66:81], v[66:69], v[82:85], 0
	v_cvt_pk_bf16_f32 v138, v42, v43
	v_cvt_pk_bf16_f32 v139, v44, v45
	v_cvt_pk_bf16_f32 v140, v46, v47
	v_cvt_pk_bf16_f32 v141, v48, v49
	v_cvt_pk_bf16_f32 v118, v50, v51
	v_cvt_pk_bf16_f32 v119, v52, v53
	v_cvt_pk_bf16_f32 v120, v54, v55
	v_mfma_f32_32x32x16_bf16 v[66:81], v[86:89], v[138:141], v[66:81]
	v_cvt_pk_bf16_f32 v121, v56, v57
	v_cvt_pk_bf16_f32 v122, v58, v59
	v_cvt_pk_bf16_f32 v123, v60, v61
	v_cvt_pk_bf16_f32 v124, v62, v63
	v_cvt_pk_bf16_f32 v125, v64, v65
	v_cvt_pk_bf16_f32 v126, v18, v19
	v_cvt_pk_bf16_f32 v127, v20, v21
	v_mfma_f32_32x32x16_bf16 v[66:81], v[90:93], v[118:121], v[66:81]
	v_cvt_pk_bf16_f32 v128, v22, v23
	v_cvt_pk_bf16_f32 v129, v24, v25
	v_cvt_pk_bf16_f32 v130, v26, v27
	v_cvt_pk_bf16_f32 v131, v28, v29
	v_cvt_pk_bf16_f32 v132, v30, v31
	v_cvt_pk_bf16_f32 v133, v32, v33
	v_cvt_pk_bf16_f32 v134, v2, v3
	v_mfma_f32_32x32x16_bf16 v[66:81], v[94:97], v[122:125], v[66:81]
	v_cvt_pk_bf16_f32 v135, v4, v5
	v_cvt_pk_bf16_f32 v136, v6, v7
	v_cvt_pk_bf16_f32 v137, v8, v9
	v_cvt_pk_bf16_f32 v114, v10, v11
	v_cvt_pk_bf16_f32 v115, v12, v13
	v_cvt_pk_bf16_f32 v116, v14, v15
	v_cvt_pk_bf16_f32 v117, v16, v17
	v_mfma_f32_32x32x16_bf16 v[82:97], v[206:209], v[82:85], 0
	v_add_u32_e32 v201, s20, v200
	s_mov_b32 s20, 0x24400000
	v_mfma_f32_32x32x16_bf16 v[82:97], v[170:173], v[138:141], v[82:97]
	v_mfma_f32_32x32x16_bf16 v[82:97], v[146:149], v[118:121], v[82:97]
	v_mfma_f32_32x32x16_bf16 v[82:97], v[150:153], v[122:125], v[82:97]
	v_mfma_f32_32x32x16_bf16 v[82:97], v[154:157], v[126:129], v[82:97]
	v_mfma_f32_32x32x16_bf16 v[82:97], v[158:161], v[130:133], v[82:97]
	v_mfma_f32_32x32x16_bf16 v[66:81], v[174:177], v[126:129], v[66:81]
	v_mfma_f32_32x32x16_bf16 v[82:97], v[162:165], v[134:137], v[82:97]
	v_mfma_f32_32x32x16_bf16 v[66:81], v[178:181], v[130:133], v[66:81]
	v_mfma_f32_32x32x16_bf16 v[82:97], v[166:169], v[114:117], v[82:97]
	v_mfma_f32_32x32x16_bf16 v[66:81], v[202:205], v[134:137], v[66:81]
	ds_read_b128 v[134:137], v0 offset:32768
	ds_read_b128 v[178:181], v0 offset:33792
	ds_read_b128 v[118:121], v0 offset:36864
	ds_read_b128 v[122:125], v0 offset:37888
	ds_read_b128 v[126:129], v0 offset:38912
	ds_read_b128 v[130:133], v0 offset:39936
	s_waitcnt lgkmcnt(0)
	v_mfma_f32_32x32x16_bf16 v[82:97], v[118:121], v[110:113], v[82:97]
	v_mfma_f32_32x32x16_bf16 v[66:81], v[142:145], v[114:117], v[66:81]
	v_mfma_f32_32x32x16_bf16 v[82:97], v[122:125], v[106:109], v[82:97]
	v_mfma_f32_32x32x16_bf16 v[66:81], v[134:137], v[110:113], v[66:81]
	ds_read_b128 v[114:117], v201 offset:57472
	ds_read_b128 v[134:137], v201 offset:57600
	ds_read_b128 v[138:141], v201 offset:57728
	ds_read_b128 v[142:145], v201 offset:57344
	ds_read_b128 v[146:149], v201 offset:57376
	ds_read_b128 v[150:153], v201 offset:57504
	ds_read_b128 v[154:157], v201 offset:57632
	ds_read_b128 v[158:161], v201 offset:57760
	ds_read_b128 v[162:165], v201 offset:57408
	ds_read_b128 v[166:169], v201 offset:57536
	ds_read_b128 v[170:173], v201 offset:57664
	ds_read_b128 v[174:177], v201 offset:57792
	ds_read_b128 v[202:205], v201 offset:57440
	ds_read_b128 v[206:209], v201 offset:57568
	ds_read_b128 v[210:213], v201 offset:57696
	ds_read_b128 v[236:239], v201 offset:57824
	s_waitcnt lgkmcnt(0)
; #define LAS __attribute__((address_space(3)))
; __device__ __forceinline__ unsigned f2bf(float f) { return cvtpk(f, 0.f) & 0xffffu; }
; #define MFMA32(a, b, c) __builtin_amdgcn_mfma_f32_32x32x16_bf16((a), (b), (c), 0, 0, 0)
; __device__ __forceinline__ int crow(int reg, int h) { return (reg & 3) + 8 * (reg >> 2) + 4 * h; }
; __device__ __forceinline__ void phase_ab_rec(const KP kp, const int bid, const int G, int j, int li, LAS unsigned char* lds, int tid0) {
;     ...
;                     for (int q = 0; q < 4; ++q) { const f32x4 g0 = *(const LAS f32x4*)(ge + 8 * q), g1 = *(const LAS f32x4*)(ge + 32 + 8 * q), g2 = *(const LAS f32x4*)(ge + 64 + 8 * q), g3 = *(const LAS f32x4*)(ge + 96 + 8 * q);
; #pragma unroll
;                         for (int c = 0; c < 4; ++c) { S0[4 * q + c] *= g0[c]; S1[4 * q + c] *= g1[c]; S2[4 * q + c] *= g2[c]; S3[4 * q + c] *= g3[c]; } }
; #pragma unroll
;                     for (int ks = 0; ks < 4; ++ks) { S0 = MFMA32(F[(16 + ks) * 64], vb[ks], S0); S1 = MFMA32(F[(20 + ks) * 64], vb[ks], S1); S2 = MFMA32(F[(24 + ks) * 64], vb[ks], S2); S3 = MFMA32(F[(28 + ks) * 64], vb[ks], S3); }
;                     bf16* yo = OGLA + (size_t)(b * 2048 + n * 64) * 1024 + h * 256 + 32 * nt + r;
; #pragma unroll
;                     for (int i = 0; i < 16; ++i) { yo[(size_t)crow(i, hp) * 1024] = (bf16)f2bf(O0[i]); yo[(size_t)(32 + crow(i, hp)) * 1024] = (bf16)f2bf(O1[i]); }
	v_pk_mul_f32 v[44:45], v[44:45], v[164:165]
	v_pk_mul_f32 v[46:47], v[46:47], v[202:203]
	v_pk_mul_f32 v[48:49], v[48:49], v[204:205]
	v_pk_mul_f32 v[40:41], v[40:41], v[148:149]
	v_pk_mul_f32 v[36:37], v[36:37], v[144:145]
	v_pk_mul_f32 v[42:43], v[42:43], v[162:163]
	v_mfma_f32_32x32x16_bf16 v[82:97], v[126:129], v[102:105], v[82:97]
	v_mul_f32_e64 v38, v38, v146
	v_mul_f32_e64 v39, v39, v147
	v_mul_f32_e64 v34, v34, v142
	v_mul_f32_e64 v35, v35, v143
	v_mul_f32_e64 v60, v60, v168
	v_mul_f32_e64 v61, v61, v169
	v_pk_mul_f32 v[56:57], v[56:57], v[152:153]
	v_pk_mul_f32 v[52:53], v[52:53], v[116:117]
	v_pk_mul_f32 v[62:63], v[62:63], v[206:207]
	v_pk_mul_f32 v[58:59], v[58:59], v[166:167]
	v_mfma_f32_32x32x16_bf16 v[66:81], v[178:181], v[106:109], v[66:81]
	v_lshl_add_u64 v[178:179], v[196:197], 0, s[8:9]
	v_add_co_u32_e32 v180, vcc, s20, v178
	s_mov_b32 s20, 0x24401000
	s_nop 0
	v_addc_co_u32_e32 v181, vcc, 0, v179, vcc
	v_add_co_u32_e32 v202, vcc, s20, v178
	v_mfma_f32_32x32x16_bf16 v[82:97], v[130:133], v[98:101], v[82:97]
	s_nop 0
	v_addc_co_u32_e32 v203, vcc, 0, v179, vcc
	s_mov_b32 s20, 0x24410000
	v_add_co_u32_e32 v204, vcc, s20, v178
	s_mov_b32 s20, 0x24411000
	s_nop 0
	v_addc_co_u32_e32 v205, vcc, 0, v179, vcc
	v_pk_mul_f32 v[54:55], v[54:55], v[150:151]
	v_pk_mul_f32 v[50:51], v[50:51], v[114:115]
	v_pk_mul_f32 v[28:29], v[28:29], v[172:173]
	v_pk_mul_f32 v[24:25], v[24:25], v[156:157]
	v_pk_mul_f32 v[20:21], v[20:21], v[136:137]
	v_pk_mul_f32 v[26:27], v[26:27], v[170:171]
	v_pk_mul_f32 v[22:23], v[22:23], v[154:155]
	v_pk_mul_f32 v[18:19], v[18:19], v[134:135]
	v_pk_mul_f32 v[12:13], v[12:13], v[176:177]
	v_pk_mul_f32 v[8:9], v[8:9], v[160:161]
	v_pk_mul_f32 v[4:5], v[4:5], v[140:141]
	v_pk_mul_f32 v[10:11], v[10:11], v[174:175]
	v_pk_mul_f32 v[6:7], v[6:7], v[158:159]
	v_pk_mul_f32 v[2:3], v[2:3], v[138:139]
	ds_read_b128 v[174:177], v0 offset:16384
	ds_read_b128 v[170:173], v0 offset:20480
	ds_read_b128 v[166:169], v0 offset:24576
	ds_read_b128 v[162:165], v0 offset:28672
	ds_read_b128 v[158:161], v0 offset:17408
	ds_read_b128 v[154:157], v0 offset:21504
	ds_read_b128 v[150:153], v0 offset:25600
	ds_read_b128 v[146:149], v0 offset:29696
	ds_read_b128 v[142:145], v0 offset:18432
	ds_read_b128 v[138:141], v0 offset:22528
	ds_read_b128 v[134:137], v0 offset:26624
	ds_read_b128 v[130:133], v0 offset:30720
	ds_read_b128 v[126:129], v0 offset:19456
	ds_read_b128 v[122:125], v0 offset:23552
	ds_read_b128 v[118:121], v0 offset:27648
	ds_read_b128 v[114:117], v0 offset:31744
	v_cvt_pk_bf16_f32 v0, v66, s0
	v_add_co_u32_e32 v206, vcc, s20, v178
	global_store_short v[202:203], v0, off offset:-4096
	v_cvt_pk_bf16_f32 v0, v82, s0
	v_addc_co_u32_e32 v207, vcc, 0, v179, vcc
	global_store_short v[206:207], v0, off offset:-4096
	v_cvt_pk_bf16_f32 v0, v67, s0
	s_mov_b32 s20, 0x24404000
	global_store_short v[180:181], v0, off offset:2048
	v_cvt_pk_bf16_f32 v0, v83, s0
	v_add_co_u32_e32 v66, vcc, s20, v178
	global_store_short v[204:205], v0, off offset:2048
	v_cvt_pk_bf16_f32 v0, v68, s0
	v_addc_co_u32_e32 v67, vcc, 0, v179, vcc
	s_mov_b32 s20, 0x24405000
	global_store_short v[202:203], v0, off
	v_cvt_pk_bf16_f32 v0, v84, s0
	v_add_co_u32_e32 v68, vcc, s20, v178
	v_pk_mul_f32 v[64:65], v[64:65], v[208:209]
	v_pk_mul_f32 v[32:33], v[32:33], v[212:213]
	v_pk_mul_f32 v[30:31], v[30:31], v[210:211]
	v_pk_mul_f32 v[16:17], v[16:17], v[238:239]
	v_pk_mul_f32 v[14:15], v[14:15], v[236:237]
	global_store_short v[206:207], v0, off
	v_cvt_pk_bf16_f32 v0, v69, s0
	v_addc_co_u32_e32 v69, vcc, 0, v179, vcc
	s_mov_b32 s20, 0x24414000
	v_add_co_u32_e32 v82, vcc, s20, v178
	s_waitcnt lgkmcnt(0)
; __device__ __forceinline__ unsigned f2bf(float f) { return cvtpk(f, 0.f) & 0xffffu; }
; #define MFMA32(a, b, c) __builtin_amdgcn_mfma_f32_32x32x16_bf16((a), (b), (c), 0, 0, 0)
; __device__ __forceinline__ int crow(int reg, int h) { return (reg & 3) + 8 * (reg >> 2) + 4 * h; }
; __device__ __forceinline__ void phase_ab_rec(const KP kp, const int bid, const int G, int j, int li, LAS unsigned char* lds, int tid0) {
;     ...
; #pragma unroll
;                     for (int ks = 0; ks < 4; ++ks) { S0 = MFMA32(F[(16 + ks) * 64], vb[ks], S0); S1 = MFMA32(F[(20 + ks) * 64], vb[ks], S1); S2 = MFMA32(F[(24 + ks) * 64], vb[ks], S2); S3 = MFMA32(F[(28 + ks) * 64], vb[ks], S3); }
;                     bf16* yo = OGLA + (size_t)(b * 2048 + n * 64) * 1024 + h * 256 + 32 * nt + r;
; #pragma unroll
;                     for (int i = 0; i < 16; ++i) { yo[(size_t)crow(i, hp) * 1024] = (bf16)f2bf(O0[i]); yo[(size_t)(32 + crow(i, hp)) * 1024] = (bf16)f2bf(O1[i]); }
;                 }
;                 asm volatile("s_waitcnt vmcnt(0)" ::: "memory"); __syncthreads();
	v_mfma_f32_32x32x16_bf16 v[34:49], v[174:177], v[110:113], v[34:49]
	global_store_short v[202:203], v0, off offset:2048
	v_cvt_pk_bf16_f32 v0, v85, s0
	v_addc_co_u32_e32 v83, vcc, 0, v179, vcc
	s_mov_b32 s20, 0x24415000
	global_store_short v[206:207], v0, off offset:2048
	v_cvt_pk_bf16_f32 v0, v70, s0
	v_mfma_f32_32x32x16_bf16 v[50:65], v[170:173], v[110:113], v[50:65]
	v_add_co_u32_e32 v84, vcc, s20, v178
	global_store_short v[68:69], v0, off offset:-4096
	v_cvt_pk_bf16_f32 v0, v86, s0
	v_addc_co_u32_e32 v85, vcc, 0, v179, vcc
	global_store_short v[84:85], v0, off offset:-4096
	v_mfma_f32_32x32x16_bf16 v[18:33], v[166:169], v[110:113], v[18:33]
	v_cvt_pk_bf16_f32 v0, v71, s0
	global_store_short v[66:67], v0, off offset:2048
	v_cvt_pk_bf16_f32 v0, v87, s0
	global_store_short v[82:83], v0, off offset:2048
	v_cvt_pk_bf16_f32 v0, v72, s0
	s_mov_b32 s20, 0x24408000
	global_store_short v[68:69], v0, off
	v_mfma_f32_32x32x16_bf16 v[2:17], v[162:165], v[110:113], v[2:17]
	v_cvt_pk_bf16_f32 v0, v88, s0
	v_add_co_u32_e32 v66, vcc, s20, v178
	global_store_short v[84:85], v0, off
	v_cvt_pk_bf16_f32 v0, v73, s0
	v_addc_co_u32_e32 v67, vcc, 0, v179, vcc
	s_mov_b32 s20, 0x24409000
	v_mfma_f32_32x32x16_bf16 v[34:49], v[158:161], v[106:109], v[34:49]
	global_store_short v[68:69], v0, off offset:2048
	v_add_co_u32_e32 v68, vcc, s20, v178
	s_mov_b32 s20, 0x24418000
	s_nop 0
	v_addc_co_u32_e32 v69, vcc, 0, v179, vcc
	v_add_co_u32_e32 v70, vcc, s20, v178
	v_mfma_f32_32x32x16_bf16 v[50:65], v[154:157], v[106:109], v[50:65]
	v_cvt_pk_bf16_f32 v0, v89, s0
	v_addc_co_u32_e32 v71, vcc, 0, v179, vcc
	s_mov_b32 s20, 0x24419000
	global_store_short v[84:85], v0, off offset:2048
	v_cvt_pk_bf16_f32 v0, v74, s0
	v_add_co_u32_e32 v72, vcc, s20, v178
	v_mfma_f32_32x32x16_bf16 v[18:33], v[150:153], v[106:109], v[18:33]
	global_store_short v[68:69], v0, off offset:-4096
	v_cvt_pk_bf16_f32 v0, v90, s0
	v_addc_co_u32_e32 v73, vcc, 0, v179, vcc
	global_store_short v[72:73], v0, off offset:-4096
	v_cvt_pk_bf16_f32 v0, v75, s0
	global_store_short v[66:67], v0, off offset:2048
	v_mfma_f32_32x32x16_bf16 v[2:17], v[146:149], v[106:109], v[2:17]
	v_cvt_pk_bf16_f32 v0, v91, s0
	global_store_short v[70:71], v0, off offset:2048
	v_cvt_pk_bf16_f32 v0, v76, s0
	s_mov_b32 s20, 0x2440c000
	global_store_short v[68:69], v0, off
	v_cvt_pk_bf16_f32 v0, v92, s0
	v_add_co_u32_e32 v66, vcc, s20, v178
	v_mfma_f32_32x32x16_bf16 v[34:49], v[142:145], v[102:105], v[34:49]
	global_store_short v[72:73], v0, off
	v_cvt_pk_bf16_f32 v0, v77, s0
	v_addc_co_u32_e32 v67, vcc, 0, v179, vcc
	s_mov_b32 s20, 0x2440d000
	global_store_short v[68:69], v0, off offset:2048
	v_add_co_u32_e32 v68, vcc, s20, v178
	v_mfma_f32_32x32x16_bf16 v[50:65], v[138:141], v[102:105], v[50:65]
	s_nop 0
	v_addc_co_u32_e32 v69, vcc, 0, v179, vcc
	s_mov_b32 s20, 0x2441c000
	v_add_co_u32_e32 v70, vcc, s20, v178
	v_cvt_pk_bf16_f32 v0, v93, s0
	s_nop 0
	v_addc_co_u32_e32 v71, vcc, 0, v179, vcc
	v_mfma_f32_32x32x16_bf16 v[18:33], v[134:137], v[102:105], v[18:33]
	s_mov_b32 s20, 0x2441d000
	global_store_short v[72:73], v0, off offset:2048
	v_cvt_pk_bf16_f32 v0, v78, s0
	v_add_co_u32_e32 v72, vcc, s20, v178
	global_store_short v[68:69], v0, off offset:-4096
	v_cvt_pk_bf16_f32 v0, v94, s0
	v_mfma_f32_32x32x16_bf16 v[2:17], v[130:133], v[102:105], v[2:17]
	v_addc_co_u32_e32 v73, vcc, 0, v179, vcc
	global_store_short v[72:73], v0, off offset:-4096
	v_cvt_pk_bf16_f32 v0, v79, s0
	global_store_short v[66:67], v0, off offset:2048
	v_cvt_pk_bf16_f32 v0, v95, s0
	global_store_short v[70:71], v0, off offset:2048
	v_mfma_f32_32x32x16_bf16 v[34:49], v[126:129], v[98:101], v[34:49]
	v_cvt_pk_bf16_f32 v0, v80, s0
	global_store_short v[68:69], v0, off
	v_cvt_pk_bf16_f32 v0, v96, s0
	global_store_short v[72:73], v0, off
	v_cvt_pk_bf16_f32 v0, v81, s0
	global_store_short v[68:69], v0, off offset:2048
	v_cvt_pk_bf16_f32 v0, v97, s0
	v_mfma_f32_32x32x16_bf16 v[50:65], v[122:125], v[98:101], v[50:65]
	global_store_short v[72:73], v0, off offset:2048
	v_mfma_f32_32x32x16_bf16 v[18:33], v[118:121], v[98:101], v[18:33]
	v_mfma_f32_32x32x16_bf16 v[2:17], v[114:117], v[98:101], v[2:17]
	s_waitcnt vmcnt(32)
	s_branch .Lgla_scan_join

; __device__ __forceinline__ void phase_ab_rec(const KP kp, const int bid, const int G, int j, int li, LAS unsigned char* lds, int tid0) {
;     ...
;             for (int n = 0; n < 32; ++n) {
;                 if (n + 1 < 32) DN_DMA(n + 1, (n + 1) & 1);
;     ...
;                 asm volatile("s_waitcnt vmcnt(0)" ::: "memory"); __syncthreads();
;             }
.Ldn_scan_join:
	s_add_u32 s48, s48, 0x20000
	s_addc_u32 s49, s49, 0
	s_add_i32 s1, s1, 1
	s_add_i32 s3, s3, 8
	s_cmp_eq_u32 s48, 0x400000
	s_waitcnt lgkmcnt(0)
	s_barrier
	s_cbranch_scc1 .LBB0_287

; #define LAS __attribute__((address_space(3)))
; __device__ __forceinline__ float bf2f(bf16 b) { return __uint_as_float(((unsigned)b) << 16); }
; #define MFMA32(a, b, c) __builtin_amdgcn_mfma_f32_32x32x16_bf16((a), (b), (c), 0, 0, 0)
; #define PACK_ACC(x, S_) __builtin_bit_cast(bf16x8, (u32x4){cvtpk((x)[8 * (S_)], (x)[8 * (S_) + 1]), cvtpk((x)[8 * (S_) + 2], (x)[8 * (S_) + 3]), cvtpk((x)[8 * (S_) + 4], (x)[8 * (S_) + 5]), cvtpk((x)[8 * (S_) + 6], (x)[8 * (S_) + 7])})
; __device__ __forceinline__ void phase_ab_rec(const KP kp, const int bid, const int G, int j, int li, LAS unsigned char* lds, int tid0) {
;     ...
;                 if (wave < 4) {
;                     const LAS bf16x8* F = (const LAS bf16x8*)(lds + (n & 1) * DBUF) + lane;
;                     const float gend = *(const LAS float*)(lds + (n & 1) * DBUF + 72 * 1024);
;                     const bf16x8 sb0 = PACK_ACC(S0, 0), sb1 = PACK_ACC(S0, 1), sb2 = PACK_ACC(S1, 0), sb3 = PACK_ACC(S1, 1), sb4 = PACK_ACC(S2, 0), sb5 = PACK_ACC(S2, 1), sb6 = PACK_ACC(S3, 0), sb7 = PACK_ACC(S3, 1);
;                     f32x16 U0t, U1t;
;                     { const bf16x8 a0 = F[(56 + nt * 2 + 0) * 64], a1 = F[(56 + nt * 2 + 1) * 64], c0 = F[(56 + (4 + nt) * 2 + 0) * 64], c1 = F[(56 + (4 + nt) * 2 + 1) * 64];
; #pragma unroll
;                       for (int e = 0; e < 8; ++e) { U0t[e] = bf2f((bf16)a0[e]); U0t[8 + e] = bf2f((bf16)a1[e]); U1t[e] = bf2f((bf16)c0[e]); U1t[8 + e] = bf2f((bf16)c1[e]); } }
;                     U0t = MFMA32(F[0 * 64], sb0, U0t); U0t = MFMA32(F[1 * 64], sb1, U0t); U0t = MFMA32(F[2 * 64], sb2, U0t); U0t = MFMA32(F[3 * 64], sb3, U0t);
;                     U0t = MFMA32(F[4 * 64], sb4, U0t); U0t = MFMA32(F[5 * 64], sb5, U0t); U0t = MFMA32(F[6 * 64], sb6, U0t); U0t = MFMA32(F[7 * 64], sb7, U0t);
;                     U1t = MFMA32(F[8 * 64], sb0, U1t); U1t = MFMA32(F[9 * 64], sb1, U1t); U1t = MFMA32(F[10 * 64], sb2, U1t); U1t = MFMA32(F[11 * 64], sb3, U1t);
;                     U1t = MFMA32(F[12 * 64], sb4, U1t); U1t = MFMA32(F[13 * 64], sb5, U1t); U1t = MFMA32(F[14 * 64], sb6, U1t); U1t = MFMA32(F[15 * 64], sb7, U1t);
;     ...
;                     for (int i = 0; i < 16; ++i) { S0[i] *= gend; S1[i] *= gend; S2[i] *= gend; S3[i] *= gend; }
.LBB0_285:
	s_bitcmp1_b32 s1, 0
	s_cselect_b32 s4, 0, 0x12400
	s_add_i32 s4, s4, 0
	v_lshl_add_u32 v180, v175, 4, s4
	v_add_u32_e32 v86, s0, v180
	v_add_u32_e32 v0, 0x10000, v86
	s_add_i32 s4, s4, 0x12000
	ds_read_b128 v[70:73], v86 offset:57344
	ds_read_b128 v[74:77], v86 offset:58368
	ds_read_b128 v[66:69], v0
	v_mov_b32_e32 v0, s4
	ds_read_b32 v0, v0
	ds_read_b128 v[78:81], v180
	v_cvt_pk_bf16_f32 v82, v34, v35
	v_cvt_pk_bf16_f32 v83, v36, v37
	v_cvt_pk_bf16_f32 v84, v38, v39
	v_cvt_pk_bf16_f32 v85, v40, v41
	s_waitcnt lgkmcnt(0)
	v_and_b32_e32 v99, 0xffff0000, v70
	v_lshlrev_b32_e32 v98, 16, v70
	v_and_b32_e32 v107, 0xffff0000, v74
	v_lshlrev_b32_e32 v106, 16, v74
	v_and_b32_e32 v101, 0xffff0000, v71
	v_lshlrev_b32_e32 v100, 16, v71
	v_and_b32_e32 v109, 0xffff0000, v75
	v_lshlrev_b32_e32 v108, 16, v75
	v_and_b32_e32 v103, 0xffff0000, v72
	v_lshlrev_b32_e32 v102, 16, v72
	v_and_b32_e32 v111, 0xffff0000, v76
	v_lshlrev_b32_e32 v110, 16, v76
	v_and_b32_e32 v105, 0xffff0000, v73
	v_lshlrev_b32_e32 v104, 16, v73
	v_and_b32_e32 v113, 0xffff0000, v77
	v_lshlrev_b32_e32 v112, 16, v77
	ds_read_b128 v[70:73], v180 offset:1024
	ds_read_b128 v[74:77], v180 offset:2048
	v_mfma_f32_32x32x16_bf16 v[98:113], v[78:81], v[82:85], v[98:113]
	v_cvt_pk_bf16_f32 v130, v42, v43
	v_cvt_pk_bf16_f32 v131, v44, v45
	v_cvt_pk_bf16_f32 v132, v46, v47
	v_cvt_pk_bf16_f32 v133, v48, v49
	v_cvt_pk_bf16_f32 v134, v50, v51
	v_cvt_pk_bf16_f32 v135, v52, v53
	v_cvt_pk_bf16_f32 v136, v54, v55
	s_waitcnt lgkmcnt(0)
	v_mfma_f32_32x32x16_bf16 v[98:113], v[70:73], v[130:133], v[98:113]
	v_cvt_pk_bf16_f32 v137, v56, v57
	ds_read_b128 v[70:73], v180 offset:3072
	v_cvt_pk_bf16_f32 v138, v58, v59
	v_cvt_pk_bf16_f32 v139, v60, v61
	v_cvt_pk_bf16_f32 v140, v62, v63
	v_cvt_pk_bf16_f32 v141, v64, v65
	v_cvt_pk_bf16_f32 v142, v18, v19
	v_mfma_f32_32x32x16_bf16 v[98:113], v[74:77], v[134:137], v[98:113]
	ds_read_b128 v[74:77], v180 offset:4096
	v_cvt_pk_bf16_f32 v143, v20, v21
	v_cvt_pk_bf16_f32 v144, v22, v23
	v_cvt_pk_bf16_f32 v145, v24, v25
	v_cvt_pk_bf16_f32 v146, v26, v27
	v_cvt_pk_bf16_f32 v147, v28, v29
	v_cvt_pk_bf16_f32 v148, v30, v31
	s_waitcnt lgkmcnt(0)
	v_mfma_f32_32x32x16_bf16 v[98:113], v[70:73], v[138:141], v[98:113]
	ds_read_b128 v[70:73], v180 offset:5120
	v_cvt_pk_bf16_f32 v149, v32, v33
	v_cvt_pk_bf16_f32 v150, v2, v3
	v_cvt_pk_bf16_f32 v151, v4, v5
	v_cvt_pk_bf16_f32 v152, v6, v7
	v_cvt_pk_bf16_f32 v153, v8, v9
	v_and_b32_e32 v115, 0xffff0000, v66
	v_mfma_f32_32x32x16_bf16 v[98:113], v[74:77], v[142:145], v[98:113]
	v_add_u32_e32 v74, 0x10400, v86
	ds_read_b128 v[74:77], v74
	ds_read_b128 v[78:81], v180 offset:6144
	v_lshlrev_b32_e32 v114, 16, v66
	v_and_b32_e32 v117, 0xffff0000, v67
	v_lshlrev_b32_e32 v116, 16, v67
	s_waitcnt lgkmcnt(0)
	v_and_b32_e32 v123, 0xffff0000, v74
	v_lshlrev_b32_e32 v122, 16, v74
	v_mfma_f32_32x32x16_bf16 v[98:113], v[70:73], v[146:149], v[98:113]
	ds_read_b128 v[70:73], v180 offset:7168
	v_and_b32_e32 v125, 0xffff0000, v75
	v_lshlrev_b32_e32 v124, 16, v75
	v_and_b32_e32 v119, 0xffff0000, v68
	v_lshlrev_b32_e32 v118, 16, v68
	v_and_b32_e32 v127, 0xffff0000, v76
	v_lshlrev_b32_e32 v126, 16, v76
	v_mfma_f32_32x32x16_bf16 v[98:113], v[78:81], v[150:153], v[98:113]
	ds_read_b128 v[78:81], v180 offset:8192
	v_and_b32_e32 v121, 0xffff0000, v69
	v_lshlrev_b32_e32 v120, 16, v69
	v_and_b32_e32 v129, 0xffff0000, v77
	v_lshlrev_b32_e32 v128, 16, v77
	ds_read_b128 v[66:69], v180 offset:9216
	v_cvt_pk_bf16_f32 v154, v10, v11
	s_waitcnt lgkmcnt(0)
	v_mfma_f32_32x32x16_bf16 v[114:129], v[78:81], v[82:85], v[114:129]
	v_cvt_pk_bf16_f32 v155, v12, v13
	v_cvt_pk_bf16_f32 v156, v14, v15
	v_cvt_pk_bf16_f32 v157, v16, v17
	s_mov_b32 s4, 0x22201000
	v_mul_f32_e64 v48, v48, v0
	v_mul_f32_e64 v49, v49, v0
	v_pk_mul_f32 v[46:47], v[46:47], v[0:1] op_sel_hi:[1,0]
	v_pk_mul_f32 v[44:45], v[44:45], v[0:1] op_sel_hi:[1,0]
	v_mfma_f32_32x32x16_bf16 v[114:129], v[66:69], v[130:133], v[114:129]
	v_mul_f32_e64 v42, v42, v0
	v_mul_f32_e64 v43, v43, v0
	v_mul_f32_e64 v40, v40, v0
	v_mul_f32_e64 v41, v41, v0
	v_mul_f32_e64 v38, v38, v0
	v_mul_f32_e64 v39, v39, v0
	v_pk_mul_f32 v[36:37], v[36:37], v[0:1] op_sel_hi:[1,0]
	v_pk_mul_f32 v[34:35], v[34:35], v[0:1] op_sel_hi:[1,0]
	v_pk_mul_f32 v[64:65], v[64:65], v[0:1] op_sel_hi:[1,0]
	v_pk_mul_f32 v[62:63], v[62:63], v[0:1] op_sel_hi:[1,0]
	v_mfma_f32_32x32x16_bf16 v[98:113], v[70:73], v[154:157], v[98:113]
	ds_read_b128 v[66:69], v180 offset:10240
	ds_read_b128 v[70:73], v180 offset:11264
	v_mul_f32_e64 v60, v60, v0
	v_mul_f32_e64 v61, v61, v0
	v_mul_f32_e64 v58, v58, v0
	v_mul_f32_e64 v59, v59, v0
	v_pk_mul_f32 v[56:57], v[56:57], v[0:1] op_sel_hi:[1,0]
	v_pk_mul_f32 v[54:55], v[54:55], v[0:1] op_sel_hi:[1,0]
	v_pk_mul_f32 v[52:53], v[52:53], v[0:1] op_sel_hi:[1,0]
	v_pk_mul_f32 v[50:51], v[50:51], v[0:1] op_sel_hi:[1,0]
	s_waitcnt lgkmcnt(0)
	v_mfma_f32_32x32x16_bf16 v[114:129], v[66:69], v[134:137], v[114:129]
	v_cvt_pk_bf16_f32 v106, v106, v107
	v_cvt_pk_bf16_f32 v107, v108, v109
	v_cvt_pk_bf16_f32 v108, v110, v111
	v_cvt_pk_bf16_f32 v109, v112, v113
	v_mul_f32_e64 v32, v32, v0
	v_mul_f32_e64 v33, v33, v0
	v_pk_mul_f32 v[30:31], v[30:31], v[0:1] op_sel_hi:[1,0]
	v_pk_mul_f32 v[28:29], v[28:29], v[0:1] op_sel_hi:[1,0]
	v_mfma_f32_32x32x16_bf16 v[114:129], v[70:73], v[138:141], v[114:129]
	ds_read_b128 v[66:69], v180 offset:12288
	ds_read_b128 v[70:73], v180 offset:13312
	v_mul_f32_e64 v26, v26, v0
	v_mul_f32_e64 v27, v27, v0
	v_mul_f32_e64 v24, v24, v0
	v_mul_f32_e64 v25, v25, v0
	v_pk_mul_f32 v[22:23], v[22:23], v[0:1] op_sel_hi:[1,0]
	v_pk_mul_f32 v[20:21], v[20:21], v[0:1] op_sel_hi:[1,0]
	v_pk_mul_f32 v[18:19], v[18:19], v[0:1] op_sel_hi:[1,0]
	v_pk_mul_f32 v[16:17], v[16:17], v[0:1] op_sel_hi:[1,0]
	s_waitcnt lgkmcnt(0)
; #define MFMA32(a, b, c) __builtin_amdgcn_mfma_f32_32x32x16_bf16((a), (b), (c), 0, 0, 0)
; __device__ __forceinline__ void phase_ab_rec(const KP kp, const int bid, const int G, int j, int li, LAS unsigned char* lds, int tid0) {
;     ...
;                     U0t = MFMA32(F[0 * 64], sb0, U0t); U0t = MFMA32(F[1 * 64], sb1, U0t); U0t = MFMA32(F[2 * 64], sb2, U0t); U0t = MFMA32(F[3 * 64], sb3, U0t);
;                     U0t = MFMA32(F[4 * 64], sb4, U0t); U0t = MFMA32(F[5 * 64], sb5, U0t); U0t = MFMA32(F[6 * 64], sb6, U0t); U0t = MFMA32(F[7 * 64], sb7, U0t);
;                     U1t = MFMA32(F[8 * 64], sb0, U1t); U1t = MFMA32(F[9 * 64], sb1, U1t); U1t = MFMA32(F[10 * 64], sb2, U1t); U1t = MFMA32(F[11 * 64], sb3, U1t);
;                     U1t = MFMA32(F[12 * 64], sb4, U1t); U1t = MFMA32(F[13 * 64], sb5, U1t); U1t = MFMA32(F[14 * 64], sb6, U1t); U1t = MFMA32(F[15 * 64], sb7, U1t);
;                     const bf16x8 ub0 = PACK_ACC(U0t, 0), ub1 = PACK_ACC(U0t, 1), ub2 = PACK_ACC(U1t, 0), ub3 = PACK_ACC(U1t, 1);
;                     f32x16 O0, O1;
; #pragma unroll
;                     for (int i = 0; i < 16; ++i) { O0[i] = 0.f; O1[i] = 0.f; }
;                     O0 = MFMA32(F[16 * 64], sb0, O0); O0 = MFMA32(F[17 * 64], sb1, O0); O0 = MFMA32(F[18 * 64], sb2, O0); O0 = MFMA32(F[19 * 64], sb3, O0);
;                     O0 = MFMA32(F[20 * 64], sb4, O0); O0 = MFMA32(F[21 * 64], sb5, O0); O0 = MFMA32(F[22 * 64], sb6, O0); O0 = MFMA32(F[23 * 64], sb7, O0);
;                     O1 = MFMA32(F[24 * 64], sb0, O1); O1 = MFMA32(F[25 * 64], sb1, O1); O1 = MFMA32(F[26 * 64], sb2, O1); O1 = MFMA32(F[27 * 64], sb3, O1);
;                     O1 = MFMA32(F[28 * 64], sb4, O1); O1 = MFMA32(F[29 * 64], sb5, O1); O1 = MFMA32(F[30 * 64], sb6, O1); O1 = MFMA32(F[31 * 64], sb7, O1);
;                     O0 = MFMA32(F[48 * 64], ub0, O0); O0 = MFMA32(F[49 * 64], ub1, O0);
;                     O1 = MFMA32(F[52 * 64], ub0, O1); O1 = MFMA32(F[53 * 64], ub1, O1); O1 = MFMA32(F[54 * 64], ub2, O1); O1 = MFMA32(F[55 * 64], ub3, O1);
; #pragma unroll
;                     for (int i = 0; i < 16; ++i) { S0[i] *= gend; S1[i] *= gend; S2[i] *= gend; S3[i] *= gend; }
;                     S0 = MFMA32(F[32 * 64], ub0, S0); S0 = MFMA32(F[33 * 64], ub1, S0); S0 = MFMA32(F[34 * 64], ub2, S0); S0 = MFMA32(F[35 * 64], ub3, S0);
	v_mfma_f32_32x32x16_bf16 v[114:129], v[66:69], v[142:145], v[114:129]
	v_mul_f32_e64 v14, v14, v0
	v_mul_f32_e64 v15, v15, v0
	v_mul_f32_e64 v12, v12, v0
	v_mul_f32_e64 v13, v13, v0
	v_mul_f32_e64 v10, v10, v0
	v_mul_f32_e64 v11, v11, v0
	v_pk_mul_f32 v[8:9], v[8:9], v[0:1] op_sel_hi:[1,0]
	v_pk_mul_f32 v[6:7], v[6:7], v[0:1] op_sel_hi:[1,0]
	v_pk_mul_f32 v[4:5], v[4:5], v[0:1] op_sel_hi:[1,0]
	v_pk_mul_f32 v[2:3], v[2:3], v[0:1] op_sel_hi:[1,0]
	v_mfma_f32_32x32x16_bf16 v[114:129], v[70:73], v[146:149], v[114:129]
	ds_read_b128 v[66:69], v180 offset:14336
	ds_read_b128 v[70:73], v180 offset:15360
	s_waitcnt lgkmcnt(0)
	v_mfma_f32_32x32x16_bf16 v[114:129], v[66:69], v[150:153], v[114:129]
	ds_read_b128 v[66:69], v180 offset:16384
	ds_read_b128 v[86:89], v180 offset:17408
	v_mfma_f32_32x32x16_bf16 v[114:129], v[70:73], v[154:157], v[114:129]
	s_waitcnt lgkmcnt(0)
	v_mfma_f32_32x32x16_bf16 v[66:81], v[66:69], v[82:85], 0
	v_mfma_f32_32x32x16_bf16 v[66:81], v[86:89], v[130:133], v[66:81]
	ds_read_b128 v[86:89], v180 offset:18432
	ds_read_b128 v[90:93], v180 offset:19456
	s_waitcnt lgkmcnt(0)
	v_mfma_f32_32x32x16_bf16 v[66:81], v[86:89], v[134:137], v[66:81]
	v_mfma_f32_32x32x16_bf16 v[66:81], v[90:93], v[138:141], v[66:81]
	ds_read_b128 v[86:89], v180 offset:20480
	ds_read_b128 v[90:93], v180 offset:21504
	s_waitcnt lgkmcnt(0)
	v_mfma_f32_32x32x16_bf16 v[66:81], v[86:89], v[142:145], v[66:81]
	v_mfma_f32_32x32x16_bf16 v[66:81], v[90:93], v[146:149], v[66:81]
	ds_read_b128 v[86:89], v180 offset:22528
	ds_read_b128 v[90:93], v180 offset:23552
	s_waitcnt lgkmcnt(0)
	v_mfma_f32_32x32x16_bf16 v[66:81], v[86:89], v[150:153], v[66:81]
	ds_read_b128 v[86:89], v180 offset:24576
	ds_read_b128 v[158:161], v180 offset:25600
	v_mfma_f32_32x32x16_bf16 v[66:81], v[90:93], v[154:157], v[66:81]
	s_waitcnt lgkmcnt(0)
	v_mfma_f32_32x32x16_bf16 v[82:97], v[86:89], v[82:85], 0
	v_mfma_f32_32x32x16_bf16 v[82:97], v[158:161], v[130:133], v[82:97]
	ds_read_b128 v[130:133], v180 offset:26624
	ds_read_b128 v[158:161], v180 offset:27648
	s_waitcnt lgkmcnt(0)
	v_mfma_f32_32x32x16_bf16 v[82:97], v[130:133], v[134:137], v[82:97]
	ds_read_b128 v[130:133], v180 offset:28672
	ds_read_b128 v[134:137], v180 offset:29696
	v_mfma_f32_32x32x16_bf16 v[82:97], v[158:161], v[138:141], v[82:97]
	s_waitcnt lgkmcnt(0)
	v_mfma_f32_32x32x16_bf16 v[82:97], v[130:133], v[142:145], v[82:97]
	v_mfma_f32_32x32x16_bf16 v[82:97], v[134:137], v[146:149], v[82:97]
	ds_read_b128 v[130:133], v180 offset:30720
	ds_read_b128 v[134:137], v180 offset:31744
	ds_read_b128 v[110:113], v180 offset:50176
	s_waitcnt lgkmcnt(0)
	v_mfma_f32_32x32x16_bf16 v[82:97], v[130:133], v[150:153], v[82:97]
	v_cvt_pk_bf16_f32 v130, v98, v99
	v_cvt_pk_bf16_f32 v131, v100, v101
	ds_read_b128 v[98:101], v180 offset:49152
	v_cvt_pk_bf16_f32 v132, v102, v103
	v_cvt_pk_bf16_f32 v102, v114, v115
	v_cvt_pk_bf16_f32 v103, v116, v117
	ds_read_b128 v[114:117], v180 offset:53248
	v_mfma_f32_32x32x16_bf16 v[82:97], v[134:137], v[154:157], v[82:97]
	v_cvt_pk_bf16_f32 v133, v104, v105
	v_cvt_pk_bf16_f32 v104, v118, v119
	v_cvt_pk_bf16_f32 v105, v120, v121
	s_waitcnt lgkmcnt(0)
	v_mfma_f32_32x32x16_bf16 v[66:81], v[98:101], v[130:133], v[66:81]
	v_cvt_pk_bf16_f32 v98, v122, v123
	v_cvt_pk_bf16_f32 v99, v124, v125
	v_cvt_pk_bf16_f32 v100, v126, v127
	v_cvt_pk_bf16_f32 v101, v128, v129
	v_mfma_f32_32x32x16_bf16 v[82:97], v[114:117], v[130:133], v[82:97]
	v_mfma_f32_32x32x16_bf16 v[66:81], v[110:113], v[106:109], v[66:81]
	ds_read_b128 v[110:113], v180 offset:54272
	ds_read_b128 v[194:197], v180 offset:55296
	ds_read_b128 v[198:201], v180 offset:56320
	ds_read_b128 v[202:205], v180 offset:32768
	ds_read_b128 v[170:173], v180 offset:33792
	ds_read_b128 v[166:169], v180 offset:34816
	ds_read_b128 v[162:165], v180 offset:35840
	ds_read_b128 v[158:161], v180 offset:36864
	ds_read_b128 v[154:157], v180 offset:37888
	ds_read_b128 v[150:153], v180 offset:38912
	ds_read_b128 v[146:149], v180 offset:39936
	ds_read_b128 v[142:145], v180 offset:40960
	ds_read_b128 v[138:141], v180 offset:41984
	v_cvt_pk_bf16_f32 v66, v66, s0
	s_waitcnt lgkmcnt(0)
; __device__ __forceinline__ unsigned f2bf(float f) { return cvtpk(f, 0.f) & 0xffffu; }
; #define MFMA32(a, b, c) __builtin_amdgcn_mfma_f32_32x32x16_bf16((a), (b), (c), 0, 0, 0)
; __device__ __forceinline__ int crow(int reg, int h) { return (reg & 3) + 8 * (reg >> 2) + 4 * h; }
; __device__ __forceinline__ void phase_ab_rec(const KP kp, const int bid, const int G, int j, int li, LAS unsigned char* lds, int tid0) {
;     ...
;                     O0 = MFMA32(F[48 * 64], ub0, O0); O0 = MFMA32(F[49 * 64], ub1, O0);
;                     O1 = MFMA32(F[52 * 64], ub0, O1); O1 = MFMA32(F[53 * 64], ub1, O1); O1 = MFMA32(F[54 * 64], ub2, O1); O1 = MFMA32(F[55 * 64], ub3, O1);
; #pragma unroll
;                     for (int i = 0; i < 16; ++i) { S0[i] *= gend; S1[i] *= gend; S2[i] *= gend; S3[i] *= gend; }
;                     S0 = MFMA32(F[32 * 64], ub0, S0); S0 = MFMA32(F[33 * 64], ub1, S0); S0 = MFMA32(F[34 * 64], ub2, S0); S0 = MFMA32(F[35 * 64], ub3, S0);
;                     S1 = MFMA32(F[36 * 64], ub0, S1); S1 = MFMA32(F[37 * 64], ub1, S1); S1 = MFMA32(F[38 * 64], ub2, S1); S1 = MFMA32(F[39 * 64], ub3, S1);
;                     S2 = MFMA32(F[40 * 64], ub0, S2); S2 = MFMA32(F[41 * 64], ub1, S2); S2 = MFMA32(F[42 * 64], ub2, S2); S2 = MFMA32(F[43 * 64], ub3, S2);
;                     S3 = MFMA32(F[44 * 64], ub0, S3); S3 = MFMA32(F[45 * 64], ub1, S3); S3 = MFMA32(F[46 * 64], ub2, S3); S3 = MFMA32(F[47 * 64], ub3, S3);
;                     bf16* yo = ODN + (size_t)(b * 2048 + n * 64) * 1024 + h * 128 + 32 * nt + r;
; #pragma unroll
;                     for (int i = 0; i < 16; ++i) { yo[(size_t)crow(i, hp) * 1024] = (bf16)f2bf(O0[i]); yo[(size_t)(32 + crow(i, hp)) * 1024] = (bf16)f2bf(O1[i]); }
;                 }
;                 asm volatile("s_waitcnt vmcnt(0)" ::: "memory"); __syncthreads();
	v_mfma_f32_32x32x16_bf16 v[82:97], v[110:113], v[106:109], v[82:97]
	ds_read_b128 v[134:137], v180 offset:43008
	ds_read_b128 v[126:129], v180 offset:44032
	ds_read_b128 v[122:125], v180 offset:45056
	ds_read_b128 v[118:121], v180 offset:46080
	ds_read_b128 v[114:117], v180 offset:47104
	ds_read_b128 v[110:113], v180 offset:48128
	v_lshl_add_u64 v[180:181], v[178:179], 0, s[48:49]
	v_cvt_pk_bf16_f32 v70, v70, s0
	v_mfma_f32_32x32x16_bf16 v[82:97], v[194:197], v[102:105], v[82:97]
	v_add_co_u32_e32 v194, vcc, s26, v180
	s_nop 1
	v_addc_co_u32_e32 v195, vcc, 0, v181, vcc
	v_add_co_u32_e32 v196, vcc, s4, v180
	v_mfma_f32_32x32x16_bf16 v[82:97], v[198:201], v[98:101], v[82:97]
	s_nop 0
	v_addc_co_u32_e32 v197, vcc, 0, v181, vcc
	v_add_co_u32_e32 v198, vcc, s66, v180
	s_mov_b32 s4, 0x22211000
	s_nop 0
	v_addc_co_u32_e32 v199, vcc, 0, v181, vcc
	v_add_co_u32_e32 v200, vcc, s4, v180
	global_store_short v[196:197], v66, off offset:-4096
	s_nop 3
	v_cvt_pk_bf16_f32 v66, v82, s0
	v_addc_co_u32_e32 v201, vcc, 0, v181, vcc
	global_store_short v[200:201], v66, off offset:-4096
	v_cvt_pk_bf16_f32 v66, v67, s0
	global_store_short v[194:195], v66, off offset:2048
	v_cvt_pk_bf16_f32 v66, v83, s0
	global_store_short v[198:199], v66, off offset:2048
	v_cvt_pk_bf16_f32 v66, v68, s0
	global_store_short v[196:197], v66, off
	v_cvt_pk_bf16_f32 v66, v84, s0
	global_store_short v[200:201], v66, off
	v_cvt_pk_bf16_f32 v66, v69, s0
	global_store_short v[196:197], v66, off offset:2048
	v_cvt_pk_bf16_f32 v66, v85, s0
	s_mov_b32 s4, 0x22204000
	global_store_short v[200:201], v66, off offset:2048
	v_add_co_u32_e32 v66, vcc, s4, v180
	s_mov_b32 s4, 0x22205000
	s_nop 0
	v_addc_co_u32_e32 v67, vcc, 0, v181, vcc
	v_add_co_u32_e32 v68, vcc, s4, v180
	s_mov_b32 s4, 0x22214000
	s_nop 0
	v_addc_co_u32_e32 v69, vcc, 0, v181, vcc
	v_add_co_u32_e32 v82, vcc, s4, v180
	s_mov_b32 s4, 0x22215000
	s_nop 0
	v_addc_co_u32_e32 v83, vcc, 0, v181, vcc
	v_add_co_u32_e32 v84, vcc, s4, v180
	global_store_short v[68:69], v70, off offset:-4096
	v_cvt_pk_bf16_f32 v70, v86, s0
	v_addc_co_u32_e32 v85, vcc, 0, v181, vcc
	global_store_short v[84:85], v70, off offset:-4096
	v_cvt_pk_bf16_f32 v70, v71, s0
	global_store_short v[66:67], v70, off offset:2048
	v_cvt_pk_bf16_f32 v66, v87, s0
	v_mfma_f32_32x32x16_bf16 v[34:49], v[202:205], v[130:133], v[34:49]
	global_store_short v[82:83], v66, off offset:2048
	v_cvt_pk_bf16_f32 v66, v72, s0
	global_store_short v[68:69], v66, off
	v_cvt_pk_bf16_f32 v66, v88, s0
	global_store_short v[84:85], v66, off
	v_cvt_pk_bf16_f32 v66, v73, s0
	global_store_short v[68:69], v66, off offset:2048
	v_mfma_f32_32x32x16_bf16 v[50:65], v[158:161], v[130:133], v[50:65]
	v_cvt_pk_bf16_f32 v66, v89, s0
	s_mov_b32 s4, 0x22208000
	global_store_short v[84:85], v66, off offset:2048
	v_add_co_u32_e32 v66, vcc, s4, v180
	s_mov_b32 s4, 0x22209000
	s_nop 0
	v_addc_co_u32_e32 v67, vcc, 0, v181, vcc
	v_mfma_f32_32x32x16_bf16 v[18:33], v[142:145], v[130:133], v[18:33]
	v_add_co_u32_e32 v68, vcc, s4, v180
	v_cvt_pk_bf16_f32 v70, v74, s0
	s_nop 0
	v_addc_co_u32_e32 v69, vcc, 0, v181, vcc
	s_mov_b32 s4, 0x22218000
	global_store_short v[68:69], v70, off offset:-4096
	s_waitcnt lgkmcnt(0)
	v_mfma_f32_32x32x16_bf16 v[2:17], v[122:125], v[130:133], v[2:17]
	v_add_co_u32_e32 v70, vcc, s4, v180
	s_mov_b32 s4, 0x22219000
	s_nop 0
	v_addc_co_u32_e32 v71, vcc, 0, v181, vcc
	v_add_co_u32_e32 v72, vcc, s4, v180
	v_mfma_f32_32x32x16_bf16 v[34:49], v[170:173], v[106:109], v[34:49]
	v_cvt_pk_bf16_f32 v74, v90, s0
	v_addc_co_u32_e32 v73, vcc, 0, v181, vcc
	global_store_short v[72:73], v74, off offset:-4096
	v_cvt_pk_bf16_f32 v74, v75, s0
	global_store_short v[66:67], v74, off offset:2048
	v_cvt_pk_bf16_f32 v66, v91, s0
	v_mfma_f32_32x32x16_bf16 v[50:65], v[154:157], v[106:109], v[50:65]
	global_store_short v[70:71], v66, off offset:2048
	v_cvt_pk_bf16_f32 v66, v76, s0
	global_store_short v[68:69], v66, off
	v_cvt_pk_bf16_f32 v66, v92, s0
	global_store_short v[72:73], v66, off
	v_cvt_pk_bf16_f32 v66, v77, s0
	global_store_short v[68:69], v66, off offset:2048
	v_mfma_f32_32x32x16_bf16 v[18:33], v[138:141], v[106:109], v[18:33]
	v_cvt_pk_bf16_f32 v66, v93, s0
	s_mov_b32 s4, 0x2220c000
	global_store_short v[72:73], v66, off offset:2048
	v_add_co_u32_e32 v66, vcc, s4, v180
	s_mov_b32 s4, 0x2220d000
	s_nop 0
	v_addc_co_u32_e32 v67, vcc, 0, v181, vcc
	v_mfma_f32_32x32x16_bf16 v[2:17], v[118:121], v[106:109], v[2:17]
	v_add_co_u32_e32 v68, vcc, s4, v180
	v_cvt_pk_bf16_f32 v70, v78, s0
	s_nop 0
	v_addc_co_u32_e32 v69, vcc, 0, v181, vcc
	s_mov_b32 s4, 0x2221c000
	global_store_short v[68:69], v70, off offset:-4096
	v_mfma_f32_32x32x16_bf16 v[34:49], v[166:169], v[102:105], v[34:49]
	v_add_co_u32_e32 v70, vcc, s4, v180
	s_mov_b32 s4, 0x2221d000
	s_nop 0
	v_addc_co_u32_e32 v71, vcc, 0, v181, vcc
	v_add_co_u32_e32 v72, vcc, s4, v180
	v_mfma_f32_32x32x16_bf16 v[50:65], v[150:153], v[102:105], v[50:65]
	v_cvt_pk_bf16_f32 v0, v94, s0
	v_addc_co_u32_e32 v73, vcc, 0, v181, vcc
	global_store_short v[72:73], v0, off offset:-4096
	v_cvt_pk_bf16_f32 v0, v79, s0
	global_store_short v[66:67], v0, off offset:2048
	v_cvt_pk_bf16_f32 v0, v95, s0
	v_mfma_f32_32x32x16_bf16 v[18:33], v[134:137], v[102:105], v[18:33]
	global_store_short v[70:71], v0, off offset:2048
	v_cvt_pk_bf16_f32 v0, v80, s0
	global_store_short v[68:69], v0, off
	v_cvt_pk_bf16_f32 v0, v96, s0
	global_store_short v[72:73], v0, off
	v_cvt_pk_bf16_f32 v0, v81, s0
	global_store_short v[68:69], v0, off offset:2048
	v_mfma_f32_32x32x16_bf16 v[2:17], v[114:117], v[102:105], v[2:17]
	v_cvt_pk_bf16_f32 v0, v97, s0
	global_store_short v[72:73], v0, off offset:2048
	v_mfma_f32_32x32x16_bf16 v[34:49], v[162:165], v[98:101], v[34:49]
	v_mfma_f32_32x32x16_bf16 v[50:65], v[146:149], v[98:101], v[50:65]
	v_mfma_f32_32x32x16_bf16 v[18:33], v[126:129], v[98:101], v[18:33]
	v_mfma_f32_32x32x16_bf16 v[2:17], v[110:113], v[98:101], v[2:17]
	s_waitcnt vmcnt(32)
	s_branch .Ldn_scan_join
